# FFN-up GEMM epilogue: removed 238 dead v_mov initialisers before full-row DPP rotates (zero-fill row_shr where the old value was 0), hazards re-padded
# speedup vs baseline: 1.0043x; 1.0043x over previous
; #define PG8_STAGE(bufoff, gbase, voff) do { _Pragma("unroll") for (int _i = 0; _i < 2; ++_i) \
;         __builtin_amdgcn_global_load_lds((const unsigned*)((const char*)(gbase) + (voff)[_i]), (LAS unsigned*)(lds + (bufoff) + ldsw + _i * 8192), 16, 0, 0); } while (0)
; #define PG8_LDA(dst, b, h) do { _Pragma("unroll") for (int m = 0; m < 4; ++m) _Pragma("unroll") for (int k = 0; k < 2; ++k) dst[m][k] = *(const LAS bf16x8*)(lds + PG8_SA(b, h) + aoff + m * 2048 + k * 1024); } while (0)
; #define PG8_LDB(dst, b, h) do { _Pragma("unroll") for (int n = 0; n < 2; ++n) _Pragma("unroll") for (int k = 0; k < 2; ++k) dst[n][k] = *(const LAS bf16x8*)(lds + PG8_SB(b, h) + boff + n * 2048 + k * 1024); } while (0)
; #define PG8_MMA(ai, bj, At, Bt) do { __builtin_amdgcn_s_setprio(1); _Pragma("unroll") for (int m = 0; m < 4; ++m) _Pragma("unroll") for (int n = 0; n < 2; ++n) _Pragma("unroll") for (int k = 0; k < 2; ++k) \
;         acc[ai][bj][m][n] = __builtin_amdgcn_mfma_f32_16x16x32_bf16(Bt[n][k], At[m][k], acc[ai][bj][m][n], 0, 0, 0); __builtin_amdgcn_s_setprio(0); } while (0)
; #define PG8_WAIT_V(n) asm volatile("s_waitcnt vmcnt(" #n ")" ::: "memory")
; #define PG8_WAIT_L(n) asm volatile("s_waitcnt lgkmcnt(" #n ")" ::: "memory")
; #define PG8_BAR __builtin_amdgcn_s_barrier()
; #define PG8_SCHED __builtin_amdgcn_sched_barrier(0)
; template <class Epi, class S_t>
; __device__ __forceinline__ void gemm_phase(LAS unsigned char* lds, int lda, int ldb, const S_t& S, const Epi& E) {
;     ...
;             PG8_LDB(B0, 0, 0); PG8_SCHED; PG8_LDA(At, 0, 0); PG8_STAGE(PG8_SA(1, 1), a1 + hstepA, voffA);
;             PG8_WAIT_L(8); PG8_BAR; PG8_WAIT_L(0); PG8_MMA(0, 0, At, B0); PG8_BAR; PG8_SCHED;
;             PG8_LDB(B1, 0, 1); PG8_STAGE(PG8_SB(0, 0), b2, voffB);
;             PG8_BAR; PG8_WAIT_L(0); PG8_MMA(0, 1, At, B1); PG8_BAR;
;             PG8_LDA(At, 0, 1); PG8_STAGE(PG8_SA(0, 0), a2, voffA);
;             PG8_BAR; PG8_WAIT_L(0); PG8_MMA(1, 0, At, B0); PG8_BAR; PG8_SCHED;
;             PG8_STAGE(PG8_SB(0, 1), b2 + hstepB, voffB);
;             PG8_WAIT_V(6); PG8_BAR; PG8_MMA(1, 1, At, B1); PG8_BAR;
.LBB0_1200:
	ds_read_b128 v[128:131], v223
	ds_read_b128 v[132:135], v223 offset:1024
	ds_read_b128 v[136:139], v223 offset:2048
	ds_read_b128 v[140:143], v223 offset:3072
	s_add_u32 s33, s74, 0xfff80080
	s_addc_u32 s43, s75, -1
	s_cmp_eq_u32 s5, 28
	s_cselect_b32 s79, s69, s43
	s_cselect_b32 s78, s68, s33
	s_cselect_b32 s77, s71, s1
	s_cselect_b32 s76, s70, s0
	s_add_i32 m0, s7, 0xc000
	ds_read_b128 v[144:147], v246
	ds_read_b128 v[148:151], v246 offset:1024
	ds_read_b128 v[152:155], v246 offset:2048
	ds_read_b128 v[156:159], v246 offset:3072
	ds_read_b128 v[160:163], v246 offset:4096
	ds_read_b128 v[164:167], v246 offset:5120
	ds_read_b128 v[168:171], v246 offset:6144
	ds_read_b128 v[172:175], v246 offset:7168
	global_load_lds_dwordx4 v236, s[74:75]
	s_add_i32 m0, s7, 0xe000
	s_nop 0
	global_load_lds_dwordx4 v238, s[74:75]
	s_waitcnt lgkmcnt(8)
	s_barrier
	s_waitcnt lgkmcnt(0)
	s_setprio 1
	s_waitcnt lgkmcnt(0)
	v_mfma_f32_16x16x32_bf16 v[124:127], v[128:131], v[144:147], v[124:127]
	v_mfma_f32_16x16x32_bf16 v[120:123], v[136:139], v[144:147], v[120:123]
	v_mfma_f32_16x16x32_bf16 v[116:119], v[128:131], v[152:155], v[116:119]
	v_mfma_f32_16x16x32_bf16 v[108:111], v[136:139], v[152:155], v[108:111]
	v_mfma_f32_16x16x32_bf16 v[100:103], v[128:131], v[160:163], v[100:103]
	v_mfma_f32_16x16x32_bf16 v[92:95], v[136:139], v[160:163], v[92:95]
	v_mfma_f32_16x16x32_bf16 v[84:87], v[128:131], v[168:171], v[84:87]
	v_mfma_f32_16x16x32_bf16 v[76:79], v[136:139], v[168:171], v[76:79]
	v_mfma_f32_16x16x32_bf16 v[124:127], v[132:135], v[148:151], v[124:127]
	v_mfma_f32_16x16x32_bf16 v[120:123], v[140:143], v[148:151], v[120:123]
	v_mfma_f32_16x16x32_bf16 v[116:119], v[132:135], v[156:159], v[116:119]
	v_mfma_f32_16x16x32_bf16 v[108:111], v[140:143], v[156:159], v[108:111]
	v_mfma_f32_16x16x32_bf16 v[100:103], v[132:135], v[164:167], v[100:103]
	v_mfma_f32_16x16x32_bf16 v[92:95], v[140:143], v[164:167], v[92:95]
	v_mfma_f32_16x16x32_bf16 v[84:87], v[132:135], v[172:175], v[84:87]
	v_mfma_f32_16x16x32_bf16 v[76:79], v[140:143], v[172:175], v[76:79]
	s_setprio 0
	s_barrier
	s_add_i32 s33, s88, s64
	s_add_u32 s98, s76, s38
	s_addc_u32 s99, s77, s39
	s_mov_b32 m0, s33
	ds_read_b128 v[176:179], v247
	ds_read_b128 v[180:183], v247 offset:1024
	ds_read_b128 v[184:187], v247 offset:2048
	ds_read_b128 v[188:191], v247 offset:3072
	global_load_lds_dwordx4 v228, s[76:77]
	s_add_i32 m0, s33, 0x2000
	s_nop 0
	global_load_lds_dwordx4 v224, s[76:77]
	s_barrier
	s_waitcnt lgkmcnt(0)
	s_setprio 1
	s_waitcnt lgkmcnt(0)
	v_mfma_f32_16x16x32_bf16 v[112:115], v[176:179], v[144:147], v[112:115]
	v_mfma_f32_16x16x32_bf16 v[104:107], v[184:187], v[144:147], v[104:107]
	v_mfma_f32_16x16x32_bf16 v[96:99], v[176:179], v[152:155], v[96:99]
	v_mfma_f32_16x16x32_bf16 v[88:91], v[184:187], v[152:155], v[88:91]
	v_mfma_f32_16x16x32_bf16 v[80:83], v[176:179], v[160:163], v[80:83]
	v_mfma_f32_16x16x32_bf16 v[72:75], v[184:187], v[160:163], v[72:75]
	v_mfma_f32_16x16x32_bf16 v[68:71], v[176:179], v[168:171], v[68:71]
	v_mfma_f32_16x16x32_bf16 v[64:67], v[184:187], v[168:171], v[64:67]
	v_mfma_f32_16x16x32_bf16 v[112:115], v[180:183], v[148:151], v[112:115]
	v_mfma_f32_16x16x32_bf16 v[104:107], v[188:191], v[148:151], v[104:107]
	v_mfma_f32_16x16x32_bf16 v[96:99], v[180:183], v[156:159], v[96:99]
	v_mfma_f32_16x16x32_bf16 v[88:91], v[188:191], v[156:159], v[88:91]
	v_mfma_f32_16x16x32_bf16 v[80:83], v[180:183], v[164:167], v[80:83]
	v_mfma_f32_16x16x32_bf16 v[72:75], v[188:191], v[164:167], v[72:75]
	v_mfma_f32_16x16x32_bf16 v[68:71], v[180:183], v[172:175], v[68:71]
	v_mfma_f32_16x16x32_bf16 v[64:67], v[188:191], v[172:175], v[64:67]
	s_setprio 0
	s_mov_b32 m0, s7
	s_add_u32 s100, s78, s38
	s_addc_u32 s101, s79, s39
	s_barrier
	ds_read_b128 v[144:147], v246 offset:16384
	ds_read_b128 v[148:151], v246 offset:17408
	ds_read_b128 v[152:155], v246 offset:18432
	ds_read_b128 v[156:159], v246 offset:19456
	ds_read_b128 v[160:163], v246 offset:20480
	ds_read_b128 v[164:167], v246 offset:21504
	ds_read_b128 v[168:171], v246 offset:22528
	ds_read_b128 v[172:175], v246 offset:23552
	global_load_lds_dwordx4 v230, s[78:79]
	s_mov_b32 m0, s35
	s_nop 0
	global_load_lds_dwordx4 v226, s[78:79]
	s_barrier
	s_waitcnt lgkmcnt(0)
	s_setprio 1
	s_waitcnt lgkmcnt(0)
	v_mfma_f32_16x16x32_bf16 v[60:63], v[128:131], v[144:147], v[60:63]
	v_mfma_f32_16x16x32_bf16 v[56:59], v[136:139], v[144:147], v[56:59]
	v_mfma_f32_16x16x32_bf16 v[52:55], v[128:131], v[152:155], v[52:55]
	v_mfma_f32_16x16x32_bf16 v[44:47], v[136:139], v[152:155], v[44:47]
	v_mfma_f32_16x16x32_bf16 v[36:39], v[128:131], v[160:163], v[36:39]
	v_mfma_f32_16x16x32_bf16 v[28:31], v[136:139], v[160:163], v[28:31]
	v_mfma_f32_16x16x32_bf16 v[20:23], v[128:131], v[168:171], v[20:23]
	v_mfma_f32_16x16x32_bf16 v[12:15], v[136:139], v[168:171], v[12:15]
	v_mfma_f32_16x16x32_bf16 v[60:63], v[132:135], v[148:151], v[60:63]
	v_mfma_f32_16x16x32_bf16 v[56:59], v[140:143], v[148:151], v[56:59]
	v_mfma_f32_16x16x32_bf16 v[52:55], v[132:135], v[156:159], v[52:55]
	v_mfma_f32_16x16x32_bf16 v[44:47], v[140:143], v[156:159], v[44:47]
	v_mfma_f32_16x16x32_bf16 v[36:39], v[132:135], v[164:167], v[36:39]
	v_mfma_f32_16x16x32_bf16 v[28:31], v[140:143], v[164:167], v[28:31]
	v_mfma_f32_16x16x32_bf16 v[20:23], v[132:135], v[172:175], v[20:23]
	v_mfma_f32_16x16x32_bf16 v[12:15], v[140:143], v[172:175], v[12:15]
	s_setprio 0
	s_barrier
	s_add_u32 s52, s76, 0x80000
	s_addc_u32 s53, s77, 0
	s_add_i32 s33, s89, s64
	s_mov_b32 m0, s33
	s_nop 0
	global_load_lds_dwordx4 v228, s[52:53]
	s_add_i32 m0, s33, 0x2000
	s_nop 0
	global_load_lds_dwordx4 v224, s[52:53]
	s_waitcnt vmcnt(6)
	s_barrier
; #define PG8_STAGE(bufoff, gbase, voff) do { _Pragma("unroll") for (int _i = 0; _i < 2; ++_i) \
;         __builtin_amdgcn_global_load_lds((const unsigned*)((const char*)(gbase) + (voff)[_i]), (LAS unsigned*)(lds + (bufoff) + ldsw + _i * 8192), 16, 0, 0); } while (0)
; #define PG8_LDA(dst, b, h) do { _Pragma("unroll") for (int m = 0; m < 4; ++m) _Pragma("unroll") for (int k = 0; k < 2; ++k) dst[m][k] = *(const LAS bf16x8*)(lds + PG8_SA(b, h) + aoff + m * 2048 + k * 1024); } while (0)
; #define PG8_LDB(dst, b, h) do { _Pragma("unroll") for (int n = 0; n < 2; ++n) _Pragma("unroll") for (int k = 0; k < 2; ++k) dst[n][k] = *(const LAS bf16x8*)(lds + PG8_SB(b, h) + boff + n * 2048 + k * 1024); } while (0)
; #define PG8_MMA(ai, bj, At, Bt) do { __builtin_amdgcn_s_setprio(1); _Pragma("unroll") for (int m = 0; m < 4; ++m) _Pragma("unroll") for (int n = 0; n < 2; ++n) _Pragma("unroll") for (int k = 0; k < 2; ++k) \
;         acc[ai][bj][m][n] = __builtin_amdgcn_mfma_f32_16x16x32_bf16(Bt[n][k], At[m][k], acc[ai][bj][m][n], 0, 0, 0); __builtin_amdgcn_s_setprio(0); } while (0)
; #define PG8_WAIT_V(n) asm volatile("s_waitcnt vmcnt(" #n ")" ::: "memory")
; #define PG8_WAIT_L(n) asm volatile("s_waitcnt lgkmcnt(" #n ")" ::: "memory")
; #define PG8_BAR __builtin_amdgcn_s_barrier()
; #define PG8_SCHED __builtin_amdgcn_sched_barrier(0)
; template <class Epi, class S_t>
; __device__ __forceinline__ void gemm_phase(LAS unsigned char* lds, int lda, int ldb, const S_t& S, const Epi& E) {
;     ...
;             PG8_WAIT_V(6); PG8_BAR; PG8_MMA(1, 1, At, B1); PG8_BAR;
;             PG8_LDB(B0, 1, 0); PG8_SCHED; PG8_LDA(At, 1, 0); PG8_STAGE(PG8_SA(0, 1), a2 + hstepA, voffA);
;             PG8_WAIT_L(8); PG8_BAR; PG8_WAIT_L(0); PG8_MMA(0, 0, At, B0); PG8_BAR; PG8_SCHED;
;             PG8_LDB(B1, 1, 1); PG8_STAGE(PG8_SB(1, 0), b3, voffB);
;             PG8_BAR; PG8_WAIT_L(0); PG8_MMA(0, 1, At, B1); PG8_BAR;
;             PG8_LDA(At, 1, 1); PG8_STAGE(PG8_SA(1, 0), a3, voffA);
;             PG8_BAR; PG8_WAIT_L(0); PG8_MMA(1, 0, At, B0); PG8_BAR; PG8_SCHED;
	s_setprio 1
	v_mfma_f32_16x16x32_bf16 v[48:51], v[176:179], v[144:147], v[48:51]
	v_mfma_f32_16x16x32_bf16 v[40:43], v[184:187], v[144:147], v[40:43]
	v_mfma_f32_16x16x32_bf16 v[32:35], v[176:179], v[152:155], v[32:35]
	v_mfma_f32_16x16x32_bf16 v[24:27], v[184:187], v[152:155], v[24:27]
	v_mfma_f32_16x16x32_bf16 v[16:19], v[176:179], v[160:163], v[16:19]
	v_mfma_f32_16x16x32_bf16 v[8:11], v[184:187], v[160:163], v[8:11]
	v_mfma_f32_16x16x32_bf16 v[4:7], v[176:179], v[168:171], v[4:7]
	v_mfma_f32_16x16x32_bf16 v[0:3], v[184:187], v[168:171], v[0:3]
	v_mfma_f32_16x16x32_bf16 v[48:51], v[180:183], v[148:151], v[48:51]
	v_mfma_f32_16x16x32_bf16 v[40:43], v[188:191], v[148:151], v[40:43]
	v_mfma_f32_16x16x32_bf16 v[32:35], v[180:183], v[156:159], v[32:35]
	v_mfma_f32_16x16x32_bf16 v[24:27], v[188:191], v[156:159], v[24:27]
	v_mfma_f32_16x16x32_bf16 v[16:19], v[180:183], v[164:167], v[16:19]
	v_mfma_f32_16x16x32_bf16 v[8:11], v[188:191], v[164:167], v[8:11]
	v_mfma_f32_16x16x32_bf16 v[4:7], v[180:183], v[172:175], v[4:7]
	v_mfma_f32_16x16x32_bf16 v[0:3], v[188:191], v[172:175], v[0:3]
	s_setprio 0
	v_add_u32_e32 v140, s90, v215
	s_barrier
	ds_read_b128 v[128:131], v140
	ds_read_b128 v[132:135], v140 offset:1024
	ds_read_b128 v[136:139], v140 offset:2048
	ds_read_b128 v[140:143], v140 offset:3072
	s_add_u32 s52, s78, 0x80000
	s_addc_u32 s53, s79, 0
	s_mov_b32 m0, s92
	ds_read_b128 v[144:147], v246 offset:32768
	ds_read_b128 v[148:151], v246 offset:33792
	ds_read_b128 v[152:155], v246 offset:34816
	ds_read_b128 v[156:159], v246 offset:35840
	ds_read_b128 v[160:163], v246 offset:36864
	ds_read_b128 v[164:167], v246 offset:37888
	ds_read_b128 v[168:171], v246 offset:38912
	ds_read_b128 v[172:175], v246 offset:39936
	global_load_lds_dwordx4 v230, s[52:53]
	s_mov_b32 m0, s50
	s_nop 0
	global_load_lds_dwordx4 v226, s[52:53]
	s_waitcnt lgkmcnt(8)
	s_barrier
	s_waitcnt lgkmcnt(0)
	s_setprio 1
	s_waitcnt lgkmcnt(0)
	v_mfma_f32_16x16x32_bf16 v[124:127], v[128:131], v[144:147], v[124:127]
	v_mfma_f32_16x16x32_bf16 v[120:123], v[136:139], v[144:147], v[120:123]
	v_mfma_f32_16x16x32_bf16 v[116:119], v[128:131], v[152:155], v[116:119]
	v_mfma_f32_16x16x32_bf16 v[108:111], v[136:139], v[152:155], v[108:111]
	v_mfma_f32_16x16x32_bf16 v[100:103], v[128:131], v[160:163], v[100:103]
	v_mfma_f32_16x16x32_bf16 v[92:95], v[136:139], v[160:163], v[92:95]
	v_mfma_f32_16x16x32_bf16 v[84:87], v[128:131], v[168:171], v[84:87]
	v_mfma_f32_16x16x32_bf16 v[76:79], v[136:139], v[168:171], v[76:79]
	v_mfma_f32_16x16x32_bf16 v[124:127], v[132:135], v[148:151], v[124:127]
	v_mfma_f32_16x16x32_bf16 v[120:123], v[140:143], v[148:151], v[120:123]
	v_mfma_f32_16x16x32_bf16 v[116:119], v[132:135], v[156:159], v[116:119]
	v_mfma_f32_16x16x32_bf16 v[108:111], v[140:143], v[156:159], v[108:111]
	v_mfma_f32_16x16x32_bf16 v[100:103], v[132:135], v[164:167], v[100:103]
	v_mfma_f32_16x16x32_bf16 v[92:95], v[140:143], v[164:167], v[92:95]
	v_mfma_f32_16x16x32_bf16 v[84:87], v[132:135], v[172:175], v[84:87]
	v_mfma_f32_16x16x32_bf16 v[76:79], v[140:143], v[172:175], v[76:79]
	s_setprio 0
	s_barrier
	s_add_i32 s33, s90, s64
	v_add_u32_e32 v188, s91, v215
	s_mov_b32 m0, s33
	ds_read_b128 v[176:179], v188
	ds_read_b128 v[180:183], v188 offset:1024
	ds_read_b128 v[184:187], v188 offset:2048
	ds_read_b128 v[188:191], v188 offset:3072
	global_load_lds_dwordx4 v228, s[98:99]
	s_add_i32 m0, s33, 0x2000
	s_nop 0
	global_load_lds_dwordx4 v224, s[98:99]
	s_barrier
	s_waitcnt lgkmcnt(0)
	s_setprio 1
	s_waitcnt lgkmcnt(0)
	v_mfma_f32_16x16x32_bf16 v[112:115], v[176:179], v[144:147], v[112:115]
	v_mfma_f32_16x16x32_bf16 v[104:107], v[184:187], v[144:147], v[104:107]
	v_mfma_f32_16x16x32_bf16 v[96:99], v[176:179], v[152:155], v[96:99]
	v_mfma_f32_16x16x32_bf16 v[88:91], v[184:187], v[152:155], v[88:91]
	v_mfma_f32_16x16x32_bf16 v[80:83], v[176:179], v[160:163], v[80:83]
	v_mfma_f32_16x16x32_bf16 v[72:75], v[184:187], v[160:163], v[72:75]
	v_mfma_f32_16x16x32_bf16 v[68:71], v[176:179], v[168:171], v[68:71]
	v_mfma_f32_16x16x32_bf16 v[64:67], v[184:187], v[168:171], v[64:67]
	v_mfma_f32_16x16x32_bf16 v[112:115], v[180:183], v[148:151], v[112:115]
	v_mfma_f32_16x16x32_bf16 v[104:107], v[188:191], v[148:151], v[104:107]
	v_mfma_f32_16x16x32_bf16 v[96:99], v[180:183], v[156:159], v[96:99]
	v_mfma_f32_16x16x32_bf16 v[88:91], v[188:191], v[156:159], v[88:91]
	v_mfma_f32_16x16x32_bf16 v[80:83], v[180:183], v[164:167], v[80:83]
	v_mfma_f32_16x16x32_bf16 v[72:75], v[188:191], v[164:167], v[72:75]
	v_mfma_f32_16x16x32_bf16 v[68:71], v[180:183], v[172:175], v[68:71]
	v_mfma_f32_16x16x32_bf16 v[64:67], v[188:191], v[172:175], v[64:67]
	s_setprio 0
	s_mov_b32 m0, s96
	s_barrier
	ds_read_b128 v[144:147], v246 offset:49152
	ds_read_b128 v[148:151], v246 offset:50176
	ds_read_b128 v[152:155], v246 offset:51200
	ds_read_b128 v[156:159], v246 offset:52224
	ds_read_b128 v[160:163], v246 offset:53248
	ds_read_b128 v[164:167], v246 offset:54272
	ds_read_b128 v[168:171], v246 offset:55296
	ds_read_b128 v[172:175], v246 offset:56320
	global_load_lds_dwordx4 v230, s[100:101]
	s_mov_b32 m0, s97
	s_nop 0
	global_load_lds_dwordx4 v226, s[100:101]
	s_barrier
; #define PG8_STAGE(bufoff, gbase, voff) do { _Pragma("unroll") for (int _i = 0; _i < 2; ++_i) \
;         __builtin_amdgcn_global_load_lds((const unsigned*)((const char*)(gbase) + (voff)[_i]), (LAS unsigned*)(lds + (bufoff) + ldsw + _i * 8192), 16, 0, 0); } while (0)
; #define PG8_WAIT_V(n) asm volatile("s_waitcnt vmcnt(" #n ")" ::: "memory")
; #define PG8_WAIT_L(n) asm volatile("s_waitcnt lgkmcnt(" #n ")" ::: "memory")
; #define PG8_BAR __builtin_amdgcn_s_barrier()
; #define PG8_SCHED __builtin_amdgcn_sched_barrier(0)
; template <class Epi, class S_t>
; __device__ __forceinline__ void gemm_phase(LAS unsigned char* lds, int lda, int ldb, const S_t& S, const Epi& E) {
;     ...
;             PG8_BAR; PG8_WAIT_L(0); PG8_MMA(1, 0, At, B0); PG8_BAR; PG8_SCHED;
;             PG8_STAGE(PG8_SB(1, 1), b3 + hstepB, voffB);
;             PG8_WAIT_V(6); PG8_BAR; PG8_MMA(1, 1, At, B1); PG8_BAR;
;     __device__ __forceinline__ void operator()(const f32x4 (&acc)[2][2][4][2], const Unit& u, int wr, int wc, int fr, int fq) const {
;     ...
;         const int j0 = u.pn * HALF + wc * 32 + 8 * fq;
;         u32x2 res0[8];
; #pragma unroll
;         for (int n = 0; n < 2; ++n) {
;             asm volatile("" ::: "memory");
;             const int jc = j0 + 4 * n;
;             const f32x4 wg0 = *(const f32x4*)(wconv + jc), wg1 = *(const f32x4*)(wconv + 2 * DFF + jc), wg2 = *(const f32x4*)(wconv + 4 * DFF + jc), bg = *(const f32x4*)(bconv + jc);
;             const f32x4 wv0 = *(const f32x4*)(wconv + DFF + jc), wv1 = *(const f32x4*)(wconv + 3 * DFF + jc), wv2 = *(const f32x4*)(wconv + 5 * DFF + jc), bv = *(const f32x4*)(bconv + DFF + jc);
; #pragma unroll
;             for (int ai = 0; ai < 2; ++ai)
; #pragma unroll
;                 for (int m = 0; m < 4; ++m) { const int row = row0 + ai * HALF + m * 16;
;                     const f32x4 g0 = acc[ai][0][m][n], v0 = acc[ai][1][m][n];
;                     f32x4 gp = (f32x4){0.f, 0.f, 0.f, 0.f}, vp = gp;
;                     if (m > 0) { gp = acc[ai][0][m > 0 ? m - 1 : 0][n]; vp = acc[ai][1][m > 0 ? m - 1 : 0][n]; }
;                     f32x4 f;
; #pragma unroll
;                     for (int j = 0; j < 4; ++j) {
;                         const float g1 = dpp_shr1(dpp_ror1(gp[j]), g0[j]), g2 = dpp_shr2(dpp_ror2(gp[j]), g0[j]);
;                         const float v1 = dpp_shr1(dpp_ror1(vp[j]), v0[j]), v2 = dpp_shr2(dpp_ror2(vp[j]), v0[j]);
	s_waitcnt lgkmcnt(0)
	s_setprio 1
	s_waitcnt lgkmcnt(0)
	v_mfma_f32_16x16x32_bf16 v[60:63], v[128:131], v[144:147], v[60:63]
	v_mfma_f32_16x16x32_bf16 v[56:59], v[136:139], v[144:147], v[56:59]
	v_mfma_f32_16x16x32_bf16 v[52:55], v[128:131], v[152:155], v[52:55]
	v_mfma_f32_16x16x32_bf16 v[44:47], v[136:139], v[152:155], v[44:47]
	v_mfma_f32_16x16x32_bf16 v[36:39], v[128:131], v[160:163], v[36:39]
	v_mfma_f32_16x16x32_bf16 v[28:31], v[136:139], v[160:163], v[28:31]
	v_mfma_f32_16x16x32_bf16 v[20:23], v[128:131], v[168:171], v[20:23]
	v_mfma_f32_16x16x32_bf16 v[12:15], v[136:139], v[168:171], v[12:15]
	v_mfma_f32_16x16x32_bf16 v[60:63], v[132:135], v[148:151], v[60:63]
	v_mfma_f32_16x16x32_bf16 v[56:59], v[140:143], v[148:151], v[56:59]
	v_mfma_f32_16x16x32_bf16 v[52:55], v[132:135], v[156:159], v[52:55]
	v_mfma_f32_16x16x32_bf16 v[44:47], v[140:143], v[156:159], v[44:47]
	v_mfma_f32_16x16x32_bf16 v[36:39], v[132:135], v[164:167], v[36:39]
	v_mfma_f32_16x16x32_bf16 v[28:31], v[140:143], v[164:167], v[28:31]
	v_mfma_f32_16x16x32_bf16 v[20:23], v[132:135], v[172:175], v[20:23]
	v_mfma_f32_16x16x32_bf16 v[12:15], v[140:143], v[172:175], v[12:15]
	s_setprio 0
	s_barrier
	s_add_u32 s52, s76, 0x80080
	s_addc_u32 s53, s77, 0
	s_add_i32 s33, s91, s64
	s_mov_b32 m0, s33
	s_nop 0
	global_load_lds_dwordx4 v228, s[52:53]
	s_add_i32 m0, s33, 0x2000
	s_nop 0
	global_load_lds_dwordx4 v224, s[52:53]
	s_waitcnt vmcnt(6)
	s_barrier
	s_setprio 1
	v_mfma_f32_16x16x32_bf16 v[48:51], v[176:179], v[144:147], v[48:51]
	v_mfma_f32_16x16x32_bf16 v[40:43], v[184:187], v[144:147], v[40:43]
	v_mfma_f32_16x16x32_bf16 v[32:35], v[176:179], v[152:155], v[32:35]
	v_mfma_f32_16x16x32_bf16 v[24:27], v[184:187], v[152:155], v[24:27]
	v_mfma_f32_16x16x32_bf16 v[16:19], v[176:179], v[160:163], v[16:19]
	v_mfma_f32_16x16x32_bf16 v[8:11], v[184:187], v[160:163], v[8:11]
	v_mfma_f32_16x16x32_bf16 v[4:7], v[176:179], v[168:171], v[4:7]
	v_mfma_f32_16x16x32_bf16 v[0:3], v[184:187], v[168:171], v[0:3]
	v_mfma_f32_16x16x32_bf16 v[48:51], v[180:183], v[148:151], v[48:51]
	v_mfma_f32_16x16x32_bf16 v[40:43], v[188:191], v[148:151], v[40:43]
	v_mfma_f32_16x16x32_bf16 v[32:35], v[180:183], v[156:159], v[32:35]
	v_mfma_f32_16x16x32_bf16 v[24:27], v[188:191], v[156:159], v[24:27]
	v_mfma_f32_16x16x32_bf16 v[16:19], v[180:183], v[164:167], v[16:19]
	v_mfma_f32_16x16x32_bf16 v[8:11], v[188:191], v[164:167], v[8:11]
	v_mfma_f32_16x16x32_bf16 v[4:7], v[180:183], v[172:175], v[4:7]
	v_mfma_f32_16x16x32_bf16 v[0:3], v[188:191], v[172:175], v[0:3]
	s_setprio 0
	s_add_i32 s5, s5, 2
	s_add_u32 s74, s74, 0x100
	s_addc_u32 s75, s75, 0
	s_add_u32 s0, s0, 0x100
	s_addc_u32 s1, s1, 0
	s_cmp_gt_u32 s5, 29
	s_barrier
	s_cbranch_scc0 .LBB0_1200
	s_lshl_b32 s5, s72, 8
	s_add_i32 s5, s5, s95
	v_or_b32_e32 v248, s5, v232
	s_cmp_lt_i32 s72, 32
	v_lshl_or_b32 v240, s42, 8, v219
	s_cbranch_scc0 .LBB0_1215
	v_lshl_or_b32 v130, s42, 7, v219
	v_ashrrev_i32_e32 v131, 31, v130
	v_readlane_b32 s16, v254, 33
	v_lshlrev_b64 v[128:129], 2, v[130:131]
	v_readlane_b32 s26, v254, 43
	v_readlane_b32 s27, v254, 44
	v_lshl_add_u64 v[132:133], s[46:47], 0, v[128:129]
	v_readlane_b32 s24, v254, 41
	v_readlane_b32 s25, v254, 42
	v_lshl_add_u64 v[176:177], s[26:27], 0, v[128:129]
	global_load_dwordx4 v[136:139], v[132:133], off
	global_load_dwordx4 v[146:149], v[176:177], off
	v_lshl_add_u64 v[132:133], s[56:57], 0, v[128:129]
	v_lshl_add_u64 v[182:183], s[24:25], 0, v[128:129]
	global_load_dwordx4 v[162:165], v[182:183], off
	global_load_dwordx4 v[150:153], v[132:133], off
	v_lshl_add_u64 v[132:133], s[54:55], 0, v[128:129]
	v_lshl_add_u64 v[134:135], s[60:61], 0, v[128:129]
	global_load_dwordx4 v[166:169], v[134:135], off
	global_load_dwordx4 v[154:157], v[132:133], off
	v_lshl_add_u64 v[132:133], s[58:59], 0, v[128:129]
	v_lshl_add_u64 v[128:129], s[48:49], 0, v[128:129]
	global_load_dwordx4 v[170:173], v[132:133], off
	global_load_dwordx4 v[158:161], v[128:129], off
	v_mov_b32_e32 v242, 0
	v_mov_b32_e32 v241, 0
	s_nop 0
	v_mov_b32_dpp v242, v242 row_ror:2 row_mask:0xf bank_mask:0xf
	v_mov_b32_dpp v241, v241 row_ror:1 row_mask:0xf bank_mask:0xf
	v_mov_b32_dpp v129, v124 row_shr:2 row_mask:0xf bank_mask:0xf bound_ctrl:1
	v_mov_b32_dpp v135, v125 row_shr:2 row_mask:0xf bank_mask:0xf bound_ctrl:1
	v_mov_b32_dpp v128, v124 row_shr:1 row_mask:0xf bank_mask:0xf bound_ctrl:1
	v_mov_b32_dpp v134, v125 row_shr:1 row_mask:0xf bank_mask:0xf bound_ctrl:1
	v_mov_b32_dpp v133, v112 row_shr:2 row_mask:0xf bank_mask:0xf bound_ctrl:1
	v_mov_b32_dpp v132, v112 row_shr:1 row_mask:0xf bank_mask:0xf bound_ctrl:1
	v_mov_b32_dpp v143, v126 row_shr:2 row_mask:0xf bank_mask:0xf bound_ctrl:1
	v_mov_b32_dpp v142, v126 row_shr:1 row_mask:0xf bank_mask:0xf bound_ctrl:1
	v_mov_b32_dpp v141, v113 row_shr:2 row_mask:0xf bank_mask:0xf bound_ctrl:1
	v_mov_b32_dpp v175, v127 row_shr:2 row_mask:0xf bank_mask:0xf bound_ctrl:1
	v_mov_b32_dpp v140, v113 row_shr:1 row_mask:0xf bank_mask:0xf bound_ctrl:1
	v_mov_b32_dpp v174, v127 row_shr:1 row_mask:0xf bank_mask:0xf bound_ctrl:1
	v_mov_b32_dpp v145, v114 row_shr:2 row_mask:0xf bank_mask:0xf bound_ctrl:1
	v_mov_b32_dpp v178, v115 row_shr:1 row_mask:0xf bank_mask:0xf bound_ctrl:1
	v_mov_b32_dpp v144, v114 row_shr:1 row_mask:0xf bank_mask:0xf bound_ctrl:1
	v_mov_b32_dpp v179, v50 row_ror:2 row_mask:0xf bank_mask:0xf
	s_nop 1
	v_mov_b32_dpp v179, v34 row_shr:2 row_mask:0xf bank_mask:0xf
	v_mov_b32_dpp v180, v51 row_ror:2 row_mask:0xf bank_mask:0xf
	v_mov_b32_dpp v181, v34 row_ror:2 row_mask:0xf bank_mask:0xf
	s_nop 0
	v_mov_b32_dpp v180, v35 row_shr:2 row_mask:0xf bank_mask:0xf
	v_mov_b32_dpp v181, v18 row_shr:2 row_mask:0xf bank_mask:0xf
	v_mov_b32_dpp v184, v35 row_ror:2 row_mask:0xf bank_mask:0xf
	v_readlane_b32 s17, v254, 34
	v_readlane_b32 s18, v254, 35
	v_mov_b32_dpp v184, v19 row_shr:2 row_mask:0xf bank_mask:0xf
	v_readlane_b32 s19, v254, 36
	v_readlane_b32 s20, v254, 37
	v_readlane_b32 s21, v254, 38
	v_readlane_b32 s22, v254, 39
	v_readlane_b32 s23, v254, 40
	v_readlane_b32 s28, v254, 45
	v_readlane_b32 s29, v254, 46
	v_readlane_b32 s30, v254, 47
	v_readlane_b32 s31, v254, 48
	s_waitcnt vmcnt(0)
; __device__ __forceinline__ unsigned pk2(float lo, float hi) { unsigned r; asm("v_cvt_pk_bf16_f32 %0, %1, %2" : "=v"(r) : "v"(lo), "v"(hi)); return r; }
; __device__ __forceinline__ float gelu_tanh(float x) { const float y = 1.5957691216f * (x + 0.044715f * x * x * x); return x * __builtin_amdgcn_rcpf(1.0f + __expf(-y)); }
; __device__ __forceinline__ float dpp_shr1(float old, float src) { return __int_as_float(__builtin_amdgcn_update_dpp(__float_as_int(old), __float_as_int(src), 0x111, 0xf, 0xf, false)); }
; __device__ __forceinline__ float dpp_shr2(float old, float src) { return __int_as_float(__builtin_amdgcn_update_dpp(__float_as_int(old), __float_as_int(src), 0x112, 0xf, 0xf, false)); }
; __device__ __forceinline__ float dpp_ror1(float src) { return __int_as_float(__builtin_amdgcn_update_dpp(0, __float_as_int(src), 0x121, 0xf, 0xf, false)); }
; __device__ __forceinline__ float dpp_ror2(float src) { return __int_as_float(__builtin_amdgcn_update_dpp(0, __float_as_int(src), 0x122, 0xf, 0xf, false)); }
;     __device__ __forceinline__ void operator()(const f32x4 (&acc)[2][2][4][2], const Unit& u, int wr, int wc, int fr, int fq) const {
;     ...
;                 for (int m = 0; m < 4; ++m) { const int row = row0 + ai * HALF + m * 16;
;                     const f32x4 g0 = acc[ai][0][m][n], v0 = acc[ai][1][m][n];
;                     f32x4 gp = (f32x4){0.f, 0.f, 0.f, 0.f}, vp = gp;
;                     if (m > 0) { gp = acc[ai][0][m > 0 ? m - 1 : 0][n]; vp = acc[ai][1][m > 0 ? m - 1 : 0][n]; }
;                     f32x4 f;
; #pragma unroll
;                     for (int j = 0; j < 4; ++j) {
;                         const float g1 = dpp_shr1(dpp_ror1(gp[j]), g0[j]), g2 = dpp_shr2(dpp_ror2(gp[j]), g0[j]);
;                         const float v1 = dpp_shr1(dpp_ror1(vp[j]), v0[j]), v2 = dpp_shr2(dpp_ror2(vp[j]), v0[j]);
;                         const float cg_ = bg[j] + g2 * wg0[j] + g1 * wg1[j] + g0[j] * wg2[j];
;                         const float cv_ = bv[j] + v2 * wv0[j] + v1 * wv1[j] + v0[j] * wv2[j];
;                         f[j] = gelu_tanh(cg_) * cv_; }
;                     u32x2 w; w.x = pk2(f[0], f[1]); w.y = pk2(f[2], f[3]);
;                     if (n == 0) res0[ai * 4 + m] = w;
	v_fma_f32 v129, v162, v129, v146
	v_fma_f32 v135, v163, v135, v147
	v_fma_f32 v133, v150, v133, v136
	v_fmac_f32_e32 v129, v166, v128
	v_fmac_f32_e32 v135, v167, v134
	v_fmac_f32_e32 v133, v154, v132
	v_fmac_f32_e32 v129, v124, v170
	v_fmac_f32_e32 v135, v125, v171
	v_mul_f32_e32 v128, 0x3d372713, v129
	v_mul_f32_e32 v132, 0x3d372713, v135
	v_mul_f32_e32 v128, v129, v128
	v_mul_f32_e32 v132, v135, v132
	v_fma_f32 v128, v129, v128, v129
	v_fma_f32 v132, v135, v132, v135
	v_mul_f32_e32 v128, 0xbfcc422a, v128
	v_mul_f32_e32 v132, 0xbfcc422a, v132
	v_mul_f32_e32 v128, 0x3fb8aa3b, v128
	v_mul_f32_e32 v132, 0x3fb8aa3b, v132
	v_exp_f32_e32 v128, v128
	v_exp_f32_e32 v132, v132
	v_fma_f32 v143, v164, v143, v148
	v_fmac_f32_e32 v143, v168, v142
	v_add_f32_e32 v128, 1.0, v128
	v_add_f32_e32 v132, 1.0, v132
	v_fmac_f32_e32 v143, v126, v172
	v_rcp_f32_e32 v128, v128
	v_rcp_f32_e32 v132, v132
	v_mul_f32_e32 v134, 0x3d372713, v143
	v_fma_f32 v141, v151, v141, v137
	v_fma_f32 v175, v165, v175, v149
	v_mul_f32_e32 v134, v143, v134
	v_fmac_f32_e32 v141, v155, v140
	v_fmac_f32_e32 v175, v169, v174
	v_fma_f32 v134, v143, v134, v143
	v_fmac_f32_e32 v133, v112, v158
	v_mul_f32_e32 v134, 0xbfcc422a, v134
	v_fmac_f32_e32 v141, v113, v159
	v_mul_f32_e32 v128, v129, v128
	v_mul_f32_e32 v129, v135, v132
	v_fmac_f32_e32 v175, v127, v173
	v_mul_f32_e32 v134, 0x3fb8aa3b, v134
	v_mul_f32_e32 v128, v133, v128
	v_mul_f32_e32 v129, v141, v129
	v_mul_f32_e32 v133, 0x3d372713, v175
	v_exp_f32_e32 v134, v134
	v_mul_f32_e32 v133, v175, v133
	v_cvt_pk_bf16_f32 v174, v128, v129
	v_fma_f32 v133, v175, v133, v175
	v_mov_b32_dpp v129, v124 row_ror:2 row_mask:0xf bank_mask:0xf
	v_mul_f32_e32 v133, 0xbfcc422a, v133
	v_mov_b32_dpp v128, v124 row_ror:1 row_mask:0xf bank_mask:0xf
	v_mov_b32_dpp v129, v116 row_shr:2 row_mask:0xf bank_mask:0xf
	v_mul_f32_e32 v133, 0x3fb8aa3b, v133
	v_mov_b32_dpp v128, v116 row_shr:1 row_mask:0xf bank_mask:0xf
	v_fma_f32 v129, v162, v129, v146
	v_add_f32_e32 v134, 1.0, v134
	v_exp_f32_e32 v133, v133
	v_fmac_f32_e32 v129, v166, v128
	v_rcp_f32_e32 v134, v134
	v_fmac_f32_e32 v129, v116, v170
	v_mul_f32_e32 v128, 0x3d372713, v129
	v_mul_f32_e32 v128, v129, v128
	v_add_f32_e32 v133, 1.0, v133
	v_fma_f32 v128, v129, v128, v129
	v_mul_f32_e32 v132, v143, v134
	v_rcp_f32_e32 v133, v133
	v_mul_f32_e32 v128, 0xbfcc422a, v128
	v_mov_b32_dpp v134, v115 row_shr:2 row_mask:0xf bank_mask:0xf bound_ctrl:1
	v_mul_f32_e32 v128, 0x3fb8aa3b, v128
	v_fma_f32 v134, v153, v134, v139
	v_exp_f32_e32 v128, v128
	v_fma_f32 v145, v152, v145, v138
	v_fmac_f32_e32 v134, v157, v178
	v_fmac_f32_e32 v145, v156, v144
	v_fmac_f32_e32 v134, v115, v161
	v_mul_f32_e32 v133, v175, v133
	v_fmac_f32_e32 v145, v114, v160
	v_mul_f32_e32 v133, v134, v133
	v_mul_f32_e32 v132, v145, v132
	v_cvt_pk_bf16_f32 v175, v132, v133
	v_add_f32_e32 v128, 1.0, v128
	v_mov_b32_dpp v133, v112 row_ror:2 row_mask:0xf bank_mask:0xf
	v_rcp_f32_e32 v128, v128
	v_mov_b32_dpp v132, v112 row_ror:1 row_mask:0xf bank_mask:0xf
	v_mov_b32_dpp v133, v96 row_shr:2 row_mask:0xf bank_mask:0xf
	v_fma_f32 v133, v150, v133, v136
	v_mov_b32_dpp v132, v96 row_shr:1 row_mask:0xf bank_mask:0xf
	v_fmac_f32_e32 v133, v154, v132
	v_mul_f32_e32 v128, v129, v128
	v_mov_b32_dpp v132, v125 row_ror:2 row_mask:0xf bank_mask:0xf
	v_fmac_f32_e32 v133, v96, v158
	v_mov_b32_dpp v129, v125 row_ror:1 row_mask:0xf bank_mask:0xf
	v_mov_b32_dpp v132, v117 row_shr:2 row_mask:0xf bank_mask:0xf
	v_fma_f32 v132, v163, v132, v147
	v_mov_b32_dpp v129, v117 row_shr:1 row_mask:0xf bank_mask:0xf
	v_fmac_f32_e32 v132, v167, v129
	v_fmac_f32_e32 v132, v117, v171
	v_mul_f32_e32 v129, 0x3d372713, v132
	v_mul_f32_e32 v129, v132, v129
	v_fma_f32 v129, v132, v129, v132
	v_mul_f32_e32 v129, 0xbfcc422a, v129
	v_mul_f32_e32 v129, 0x3fb8aa3b, v129
	v_exp_f32_e32 v129, v129
	v_mul_f32_e32 v128, v133, v128
	v_add_f32_e32 v129, 1.0, v129
	v_mov_b32_dpp v134, v113 row_ror:2 row_mask:0xf bank_mask:0xf
	v_rcp_f32_e32 v129, v129
	v_mov_b32_dpp v133, v113 row_ror:1 row_mask:0xf bank_mask:0xf
	v_mov_b32_dpp v134, v97 row_shr:2 row_mask:0xf bank_mask:0xf
	v_fma_f32 v134, v151, v134, v137
	v_mov_b32_dpp v133, v97 row_shr:1 row_mask:0xf bank_mask:0xf
	v_fmac_f32_e32 v134, v155, v133
	v_mul_f32_e32 v129, v132, v129
	v_mov_b32_dpp v133, v126 row_ror:2 row_mask:0xf bank_mask:0xf
	v_fmac_f32_e32 v134, v97, v159
	v_mov_b32_dpp v132, v126 row_ror:1 row_mask:0xf bank_mask:0xf
	v_mov_b32_dpp v133, v118 row_shr:2 row_mask:0xf bank_mask:0xf
	v_fma_f32 v133, v164, v133, v148
	v_mov_b32_dpp v132, v118 row_shr:1 row_mask:0xf bank_mask:0xf
	v_fmac_f32_e32 v133, v168, v132
	v_fmac_f32_e32 v133, v118, v172
	v_mul_f32_e32 v132, 0x3d372713, v133
	v_mul_f32_e32 v132, v133, v132
	v_fma_f32 v132, v133, v132, v133
	v_mul_f32_e32 v132, 0xbfcc422a, v132
	v_mul_f32_e32 v132, 0x3fb8aa3b, v132
	v_exp_f32_e32 v132, v132
	v_mul_f32_e32 v129, v134, v129
	v_add_f32_e32 v132, 1.0, v132
	v_mov_b32_dpp v135, v114 row_ror:2 row_mask:0xf bank_mask:0xf
	v_rcp_f32_e32 v132, v132
	v_mov_b32_dpp v134, v114 row_ror:1 row_mask:0xf bank_mask:0xf
	v_mov_b32_dpp v135, v98 row_shr:2 row_mask:0xf bank_mask:0xf
	v_fma_f32 v135, v152, v135, v138
	v_mov_b32_dpp v134, v98 row_shr:1 row_mask:0xf bank_mask:0xf
	v_fmac_f32_e32 v135, v156, v134
	v_mul_f32_e32 v132, v133, v132
	v_mov_b32_dpp v134, v127 row_ror:2 row_mask:0xf bank_mask:0xf
	v_cvt_pk_bf16_f32 v144, v128, v129
	v_mov_b32_dpp v133, v127 row_ror:1 row_mask:0xf bank_mask:0xf
	v_mov_b32_dpp v134, v119 row_shr:2 row_mask:0xf bank_mask:0xf
	v_fma_f32 v134, v165, v134, v149
	v_mov_b32_dpp v133, v119 row_shr:1 row_mask:0xf bank_mask:0xf
	v_fmac_f32_e32 v134, v169, v133
; __device__ __forceinline__ unsigned pk2(float lo, float hi) { unsigned r; asm("v_cvt_pk_bf16_f32 %0, %1, %2" : "=v"(r) : "v"(lo), "v"(hi)); return r; }
; __device__ __forceinline__ float gelu_tanh(float x) { const float y = 1.5957691216f * (x + 0.044715f * x * x * x); return x * __builtin_amdgcn_rcpf(1.0f + __expf(-y)); }
; __device__ __forceinline__ float dpp_shr1(float old, float src) { return __int_as_float(__builtin_amdgcn_update_dpp(__float_as_int(old), __float_as_int(src), 0x111, 0xf, 0xf, false)); }
; __device__ __forceinline__ float dpp_shr2(float old, float src) { return __int_as_float(__builtin_amdgcn_update_dpp(__float_as_int(old), __float_as_int(src), 0x112, 0xf, 0xf, false)); }
; __device__ __forceinline__ float dpp_ror1(float src) { return __int_as_float(__builtin_amdgcn_update_dpp(0, __float_as_int(src), 0x121, 0xf, 0xf, false)); }
; __device__ __forceinline__ float dpp_ror2(float src) { return __int_as_float(__builtin_amdgcn_update_dpp(0, __float_as_int(src), 0x122, 0xf, 0xf, false)); }
;     __device__ __forceinline__ void operator()(const f32x4 (&acc)[2][2][4][2], const Unit& u, int wr, int wc, int fr, int fq) const {
;     ...
;                 for (int m = 0; m < 4; ++m) { const int row = row0 + ai * HALF + m * 16;
;                     const f32x4 g0 = acc[ai][0][m][n], v0 = acc[ai][1][m][n];
;                     f32x4 gp = (f32x4){0.f, 0.f, 0.f, 0.f}, vp = gp;
;                     if (m > 0) { gp = acc[ai][0][m > 0 ? m - 1 : 0][n]; vp = acc[ai][1][m > 0 ? m - 1 : 0][n]; }
;                     f32x4 f;
; #pragma unroll
;                     for (int j = 0; j < 4; ++j) {
;                         const float g1 = dpp_shr1(dpp_ror1(gp[j]), g0[j]), g2 = dpp_shr2(dpp_ror2(gp[j]), g0[j]);
;                         const float v1 = dpp_shr1(dpp_ror1(vp[j]), v0[j]), v2 = dpp_shr2(dpp_ror2(vp[j]), v0[j]);
;                         const float cg_ = bg[j] + g2 * wg0[j] + g1 * wg1[j] + g0[j] * wg2[j];
;                         const float cv_ = bv[j] + v2 * wv0[j] + v1 * wv1[j] + v0[j] * wv2[j];
;                         f[j] = gelu_tanh(cg_) * cv_; }
;                     u32x2 w; w.x = pk2(f[0], f[1]); w.y = pk2(f[2], f[3]);
;                     if (n == 0) res0[ai * 4 + m] = w;
	v_fmac_f32_e32 v134, v119, v173
	v_mul_f32_e32 v133, 0x3d372713, v134
	v_mul_f32_e32 v133, v134, v133
	v_fma_f32 v133, v134, v133, v134
	v_mov_b32_dpp v129, v116 row_ror:2 row_mask:0xf bank_mask:0xf
	v_mul_f32_e32 v133, 0xbfcc422a, v133
	v_mov_b32_dpp v128, v116 row_ror:1 row_mask:0xf bank_mask:0xf
	v_mov_b32_dpp v129, v100 row_shr:2 row_mask:0xf bank_mask:0xf
	v_mul_f32_e32 v133, 0x3fb8aa3b, v133
	v_mov_b32_dpp v128, v100 row_shr:1 row_mask:0xf bank_mask:0xf
	v_fma_f32 v129, v162, v129, v146
	v_exp_f32_e32 v133, v133
	v_fmac_f32_e32 v129, v166, v128
	v_fmac_f32_e32 v129, v100, v170
	v_mul_f32_e32 v128, 0x3d372713, v129
	v_mul_f32_e32 v128, v129, v128
	v_fmac_f32_e32 v135, v98, v160
	v_add_f32_e32 v133, 1.0, v133
	v_fma_f32 v128, v129, v128, v129
	v_mul_f32_e32 v132, v135, v132
	v_mov_b32_dpp v140, v115 row_ror:2 row_mask:0xf bank_mask:0xf
	v_rcp_f32_e32 v133, v133
	v_mul_f32_e32 v128, 0xbfcc422a, v128
	v_mov_b32_dpp v135, v115 row_ror:1 row_mask:0xf bank_mask:0xf
	v_mov_b32_dpp v140, v99 row_shr:2 row_mask:0xf bank_mask:0xf
	v_mul_f32_e32 v128, 0x3fb8aa3b, v128
	v_mov_b32_dpp v135, v99 row_shr:1 row_mask:0xf bank_mask:0xf
	v_fma_f32 v140, v153, v140, v139
	v_exp_f32_e32 v128, v128
	v_fmac_f32_e32 v140, v157, v135
	v_fmac_f32_e32 v140, v99, v161
	v_mul_f32_e32 v133, v134, v133
	v_mul_f32_e32 v133, v140, v133
	v_cvt_pk_bf16_f32 v145, v132, v133
	v_add_f32_e32 v128, 1.0, v128
	v_mov_b32_dpp v133, v96 row_ror:2 row_mask:0xf bank_mask:0xf
	v_rcp_f32_e32 v128, v128
	v_mov_b32_dpp v132, v96 row_ror:1 row_mask:0xf bank_mask:0xf
	v_mov_b32_dpp v133, v80 row_shr:2 row_mask:0xf bank_mask:0xf
	v_fma_f32 v133, v150, v133, v136
	v_mov_b32_dpp v132, v80 row_shr:1 row_mask:0xf bank_mask:0xf
	v_fmac_f32_e32 v133, v154, v132
	v_mul_f32_e32 v128, v129, v128
	v_mov_b32_dpp v132, v117 row_ror:2 row_mask:0xf bank_mask:0xf
	v_fmac_f32_e32 v133, v80, v158
	v_mov_b32_dpp v129, v117 row_ror:1 row_mask:0xf bank_mask:0xf
	v_mov_b32_dpp v132, v101 row_shr:2 row_mask:0xf bank_mask:0xf
	v_fma_f32 v132, v163, v132, v147
	v_mov_b32_dpp v129, v101 row_shr:1 row_mask:0xf bank_mask:0xf
	v_fmac_f32_e32 v132, v167, v129
	v_fmac_f32_e32 v132, v101, v171
	v_mul_f32_e32 v129, 0x3d372713, v132
	v_mul_f32_e32 v129, v132, v129
	v_fma_f32 v129, v132, v129, v132
	v_mul_f32_e32 v129, 0xbfcc422a, v129
	v_mul_f32_e32 v129, 0x3fb8aa3b, v129
	v_exp_f32_e32 v129, v129
	v_mul_f32_e32 v128, v133, v128
	v_add_f32_e32 v129, 1.0, v129
	v_mov_b32_dpp v134, v97 row_ror:2 row_mask:0xf bank_mask:0xf
	v_rcp_f32_e32 v129, v129
	v_mov_b32_dpp v133, v97 row_ror:1 row_mask:0xf bank_mask:0xf
	v_mov_b32_dpp v134, v81 row_shr:2 row_mask:0xf bank_mask:0xf
	v_fma_f32 v134, v151, v134, v137
	v_mov_b32_dpp v133, v81 row_shr:1 row_mask:0xf bank_mask:0xf
	v_fmac_f32_e32 v134, v155, v133
	v_mul_f32_e32 v129, v132, v129
	v_mov_b32_dpp v133, v118 row_ror:2 row_mask:0xf bank_mask:0xf
	v_fmac_f32_e32 v134, v81, v159
	v_mov_b32_dpp v132, v118 row_ror:1 row_mask:0xf bank_mask:0xf
	v_mov_b32_dpp v133, v102 row_shr:2 row_mask:0xf bank_mask:0xf
	v_fma_f32 v133, v164, v133, v148
	v_mov_b32_dpp v132, v102 row_shr:1 row_mask:0xf bank_mask:0xf
	v_fmac_f32_e32 v133, v168, v132
	v_fmac_f32_e32 v133, v102, v172
	v_mul_f32_e32 v132, 0x3d372713, v133
	v_mul_f32_e32 v132, v133, v132
	v_fma_f32 v132, v133, v132, v133
	v_mul_f32_e32 v132, 0xbfcc422a, v132
	v_mul_f32_e32 v132, 0x3fb8aa3b, v132
	v_exp_f32_e32 v132, v132
	v_mul_f32_e32 v129, v134, v129
	v_add_f32_e32 v132, 1.0, v132
	v_mov_b32_dpp v135, v98 row_ror:2 row_mask:0xf bank_mask:0xf
	v_rcp_f32_e32 v132, v132
	v_mov_b32_dpp v134, v98 row_ror:1 row_mask:0xf bank_mask:0xf
	v_mov_b32_dpp v135, v82 row_shr:2 row_mask:0xf bank_mask:0xf
	v_fma_f32 v135, v152, v135, v138
	v_mov_b32_dpp v134, v82 row_shr:1 row_mask:0xf bank_mask:0xf
	v_fmac_f32_e32 v135, v156, v134
	v_mul_f32_e32 v132, v133, v132
	v_mov_b32_dpp v134, v119 row_ror:2 row_mask:0xf bank_mask:0xf
	v_cvt_pk_bf16_f32 v142, v128, v129
	v_mov_b32_dpp v133, v119 row_ror:1 row_mask:0xf bank_mask:0xf
	v_mov_b32_dpp v134, v103 row_shr:2 row_mask:0xf bank_mask:0xf
	v_fma_f32 v134, v165, v134, v149
	v_mov_b32_dpp v133, v103 row_shr:1 row_mask:0xf bank_mask:0xf
	v_fmac_f32_e32 v134, v169, v133
	v_fmac_f32_e32 v134, v103, v173
	v_mul_f32_e32 v133, 0x3d372713, v134
	v_mul_f32_e32 v133, v134, v133
	v_fma_f32 v133, v134, v133, v134
	v_mov_b32_dpp v129, v100 row_ror:2 row_mask:0xf bank_mask:0xf
	v_mul_f32_e32 v133, 0xbfcc422a, v133
	v_mov_b32_dpp v128, v100 row_ror:1 row_mask:0xf bank_mask:0xf
	v_mov_b32_dpp v129, v84 row_shr:2 row_mask:0xf bank_mask:0xf
	v_mul_f32_e32 v133, 0x3fb8aa3b, v133
	v_mov_b32_dpp v128, v84 row_shr:1 row_mask:0xf bank_mask:0xf
	v_fma_f32 v129, v162, v129, v146
	v_exp_f32_e32 v133, v133
	v_fmac_f32_e32 v129, v166, v128
	v_fmac_f32_e32 v129, v84, v170
	v_mul_f32_e32 v128, 0x3d372713, v129
	v_mul_f32_e32 v128, v129, v128
	v_fmac_f32_e32 v135, v82, v160
	v_add_f32_e32 v133, 1.0, v133
	v_fma_f32 v128, v129, v128, v129
	v_mul_f32_e32 v132, v135, v132
	v_mov_b32_dpp v140, v99 row_ror:2 row_mask:0xf bank_mask:0xf
	v_rcp_f32_e32 v133, v133
	v_mul_f32_e32 v128, 0xbfcc422a, v128
	v_mov_b32_dpp v135, v99 row_ror:1 row_mask:0xf bank_mask:0xf
	v_mov_b32_dpp v140, v83 row_shr:2 row_mask:0xf bank_mask:0xf
	v_mul_f32_e32 v128, 0x3fb8aa3b, v128
	v_mov_b32_dpp v135, v83 row_shr:1 row_mask:0xf bank_mask:0xf
	v_fma_f32 v140, v153, v140, v139
	v_exp_f32_e32 v128, v128
	v_fmac_f32_e32 v140, v157, v135
	v_fmac_f32_e32 v140, v83, v161
	v_mul_f32_e32 v133, v134, v133
	v_mul_f32_e32 v133, v140, v133
	v_cvt_pk_bf16_f32 v143, v132, v133
	v_add_f32_e32 v128, 1.0, v128
	v_mov_b32_dpp v133, v80 row_ror:2 row_mask:0xf bank_mask:0xf
; __device__ __forceinline__ unsigned pk2(float lo, float hi) { unsigned r; asm("v_cvt_pk_bf16_f32 %0, %1, %2" : "=v"(r) : "v"(lo), "v"(hi)); return r; }
; __device__ __forceinline__ float gelu_tanh(float x) { const float y = 1.5957691216f * (x + 0.044715f * x * x * x); return x * __builtin_amdgcn_rcpf(1.0f + __expf(-y)); }
; __device__ __forceinline__ float dpp_shr1(float old, float src) { return __int_as_float(__builtin_amdgcn_update_dpp(__float_as_int(old), __float_as_int(src), 0x111, 0xf, 0xf, false)); }
; __device__ __forceinline__ float dpp_shr2(float old, float src) { return __int_as_float(__builtin_amdgcn_update_dpp(__float_as_int(old), __float_as_int(src), 0x112, 0xf, 0xf, false)); }
; __device__ __forceinline__ float dpp_ror1(float src) { return __int_as_float(__builtin_amdgcn_update_dpp(0, __float_as_int(src), 0x121, 0xf, 0xf, false)); }
; __device__ __forceinline__ float dpp_ror2(float src) { return __int_as_float(__builtin_amdgcn_update_dpp(0, __float_as_int(src), 0x122, 0xf, 0xf, false)); }
;     __device__ __forceinline__ void operator()(const f32x4 (&acc)[2][2][4][2], const Unit& u, int wr, int wc, int fr, int fq) const {
;     ...
;                 for (int m = 0; m < 4; ++m) { const int row = row0 + ai * HALF + m * 16;
;                     const f32x4 g0 = acc[ai][0][m][n], v0 = acc[ai][1][m][n];
;                     f32x4 gp = (f32x4){0.f, 0.f, 0.f, 0.f}, vp = gp;
;                     if (m > 0) { gp = acc[ai][0][m > 0 ? m - 1 : 0][n]; vp = acc[ai][1][m > 0 ? m - 1 : 0][n]; }
;                     f32x4 f;
; #pragma unroll
;                     for (int j = 0; j < 4; ++j) {
;                         const float g1 = dpp_shr1(dpp_ror1(gp[j]), g0[j]), g2 = dpp_shr2(dpp_ror2(gp[j]), g0[j]);
;                         const float v1 = dpp_shr1(dpp_ror1(vp[j]), v0[j]), v2 = dpp_shr2(dpp_ror2(vp[j]), v0[j]);
;                         const float cg_ = bg[j] + g2 * wg0[j] + g1 * wg1[j] + g0[j] * wg2[j];
;                         const float cv_ = bv[j] + v2 * wv0[j] + v1 * wv1[j] + v0[j] * wv2[j];
;                         f[j] = gelu_tanh(cg_) * cv_; }
;                     u32x2 w; w.x = pk2(f[0], f[1]); w.y = pk2(f[2], f[3]);
;                     if (n == 0) res0[ai * 4 + m] = w;
	v_rcp_f32_e32 v128, v128
	v_mov_b32_dpp v132, v80 row_ror:1 row_mask:0xf bank_mask:0xf
	v_mov_b32_dpp v133, v68 row_shr:2 row_mask:0xf bank_mask:0xf
	v_fma_f32 v133, v150, v133, v136
	v_mov_b32_dpp v132, v68 row_shr:1 row_mask:0xf bank_mask:0xf
	v_fmac_f32_e32 v133, v154, v132
	v_mul_f32_e32 v128, v129, v128
	v_mov_b32_dpp v132, v101 row_ror:2 row_mask:0xf bank_mask:0xf
	v_fmac_f32_e32 v133, v68, v158
	v_mov_b32_dpp v129, v101 row_ror:1 row_mask:0xf bank_mask:0xf
	v_mov_b32_dpp v132, v85 row_shr:2 row_mask:0xf bank_mask:0xf
	v_fma_f32 v132, v163, v132, v147
	v_mov_b32_dpp v129, v85 row_shr:1 row_mask:0xf bank_mask:0xf
	v_fmac_f32_e32 v132, v167, v129
	v_fmac_f32_e32 v132, v85, v171
	v_mul_f32_e32 v129, 0x3d372713, v132
	v_mul_f32_e32 v129, v132, v129
	v_fma_f32 v129, v132, v129, v132
	v_mul_f32_e32 v129, 0xbfcc422a, v129
	v_mul_f32_e32 v129, 0x3fb8aa3b, v129
	v_exp_f32_e32 v129, v129
	v_mul_f32_e32 v128, v133, v128
	v_add_f32_e32 v129, 1.0, v129
	v_mov_b32_dpp v134, v81 row_ror:2 row_mask:0xf bank_mask:0xf
	v_rcp_f32_e32 v129, v129
	v_mov_b32_dpp v133, v81 row_ror:1 row_mask:0xf bank_mask:0xf
	v_mov_b32_dpp v134, v69 row_shr:2 row_mask:0xf bank_mask:0xf
	v_fma_f32 v134, v151, v134, v137
	v_mov_b32_dpp v133, v69 row_shr:1 row_mask:0xf bank_mask:0xf
	v_fmac_f32_e32 v134, v155, v133
	v_mul_f32_e32 v129, v132, v129
	v_mov_b32_dpp v133, v102 row_ror:2 row_mask:0xf bank_mask:0xf
	v_fmac_f32_e32 v134, v69, v159
	v_mov_b32_dpp v132, v102 row_ror:1 row_mask:0xf bank_mask:0xf
	v_mov_b32_dpp v133, v86 row_shr:2 row_mask:0xf bank_mask:0xf
	v_fma_f32 v133, v164, v133, v148
	v_mov_b32_dpp v132, v86 row_shr:1 row_mask:0xf bank_mask:0xf
	v_fmac_f32_e32 v133, v168, v132
	v_fmac_f32_e32 v133, v86, v172
	v_mul_f32_e32 v132, 0x3d372713, v133
	v_mul_f32_e32 v132, v133, v132
	v_fma_f32 v132, v133, v132, v133
	v_mul_f32_e32 v132, 0xbfcc422a, v132
	v_mul_f32_e32 v132, 0x3fb8aa3b, v132
	v_exp_f32_e32 v132, v132
	v_mul_f32_e32 v129, v134, v129
	v_add_f32_e32 v132, 1.0, v132
	v_mov_b32_dpp v135, v82 row_ror:2 row_mask:0xf bank_mask:0xf
	v_rcp_f32_e32 v132, v132
	v_mov_b32_dpp v134, v82 row_ror:1 row_mask:0xf bank_mask:0xf
	v_mov_b32_dpp v135, v70 row_shr:2 row_mask:0xf bank_mask:0xf
	v_fma_f32 v135, v152, v135, v138
	v_mov_b32_dpp v134, v70 row_shr:1 row_mask:0xf bank_mask:0xf
	v_fmac_f32_e32 v135, v156, v134
	v_mul_f32_e32 v132, v133, v132
	v_mov_b32_dpp v134, v103 row_ror:2 row_mask:0xf bank_mask:0xf
	v_fmac_f32_e32 v135, v70, v160
	v_mov_b32_dpp v133, v103 row_ror:1 row_mask:0xf bank_mask:0xf
	v_mov_b32_dpp v134, v87 row_shr:2 row_mask:0xf bank_mask:0xf
	v_fma_f32 v134, v165, v134, v149
	v_mov_b32_dpp v133, v87 row_shr:1 row_mask:0xf bank_mask:0xf
	v_fmac_f32_e32 v134, v169, v133
	v_fmac_f32_e32 v134, v87, v173
	v_mul_f32_e32 v133, 0x3d372713, v134
	v_mul_f32_e32 v133, v134, v133
	v_fma_f32 v133, v134, v133, v134
	v_mul_f32_e32 v133, 0xbfcc422a, v133
	v_mul_f32_e32 v133, 0x3fb8aa3b, v133
	v_exp_f32_e32 v133, v133
	v_mul_f32_e32 v132, v135, v132
	v_add_f32_e32 v133, 1.0, v133
	v_mov_b32_dpp v140, v83 row_ror:2 row_mask:0xf bank_mask:0xf
	v_rcp_f32_e32 v133, v133
	v_mov_b32_dpp v135, v83 row_ror:1 row_mask:0xf bank_mask:0xf
	v_mov_b32_dpp v140, v71 row_shr:2 row_mask:0xf bank_mask:0xf
	v_fma_f32 v140, v153, v140, v139
	v_mov_b32_dpp v135, v71 row_shr:1 row_mask:0xf bank_mask:0xf
	v_fmac_f32_e32 v140, v157, v135
	v_fmac_f32_e32 v140, v71, v161
	v_mul_f32_e32 v133, v134, v133
	v_mul_f32_e32 v133, v140, v133
	v_cvt_pk_bf16_f32 v140, v128, v129
	v_cvt_pk_bf16_f32 v141, v132, v133
	v_mov_b32_dpp v129, v60 row_shr:2 row_mask:0xf bank_mask:0xf bound_ctrl:1
	v_mov_b32_dpp v128, v60 row_shr:1 row_mask:0xf bank_mask:0xf bound_ctrl:1
	v_fma_f32 v129, v162, v129, v146
	v_fmac_f32_e32 v129, v166, v128
	v_fmac_f32_e32 v129, v60, v170
	v_mul_f32_e32 v128, 0x3d372713, v129
	v_mul_f32_e32 v128, v129, v128
	v_fma_f32 v128, v129, v128, v129
	v_mul_f32_e32 v128, 0xbfcc422a, v128
	v_mul_f32_e32 v128, 0x3fb8aa3b, v128
	v_exp_f32_e32 v128, v128
	v_mov_b32_dpp v133, v48 row_shr:2 row_mask:0xf bank_mask:0xf bound_ctrl:1
	v_fma_f32 v133, v150, v133, v136
	v_add_f32_e32 v128, 1.0, v128
	v_rcp_f32_e32 v128, v128
	v_mov_b32_dpp v132, v48 row_shr:1 row_mask:0xf bank_mask:0xf bound_ctrl:1
	v_fmac_f32_e32 v133, v154, v132
	v_mul_f32_e32 v128, v129, v128
	v_mov_b32_dpp v132, v61 row_shr:2 row_mask:0xf bank_mask:0xf bound_ctrl:1
	v_fma_f32 v132, v163, v132, v147
	v_mov_b32_dpp v129, v61 row_shr:1 row_mask:0xf bank_mask:0xf bound_ctrl:1
	v_fmac_f32_e32 v132, v167, v129
	v_fmac_f32_e32 v132, v61, v171
	v_mul_f32_e32 v129, 0x3d372713, v132
	v_mul_f32_e32 v129, v132, v129
	v_fma_f32 v129, v132, v129, v132
	v_mul_f32_e32 v129, 0xbfcc422a, v129
	v_mul_f32_e32 v129, 0x3fb8aa3b, v129
	v_exp_f32_e32 v129, v129
	v_fmac_f32_e32 v133, v48, v158
	v_mul_f32_e32 v128, v133, v128
	v_add_f32_e32 v129, 1.0, v129
	v_rcp_f32_e32 v129, v129
	v_mov_b32_dpp v134, v49 row_shr:2 row_mask:0xf bank_mask:0xf bound_ctrl:1
	v_fma_f32 v134, v151, v134, v137
	v_mov_b32_dpp v133, v49 row_shr:1 row_mask:0xf bank_mask:0xf bound_ctrl:1
	v_fmac_f32_e32 v134, v155, v133
	v_mul_f32_e32 v129, v132, v129
	v_mov_b32_dpp v133, v62 row_shr:2 row_mask:0xf bank_mask:0xf bound_ctrl:1
	v_fma_f32 v133, v164, v133, v148
	v_mov_b32_dpp v132, v62 row_shr:1 row_mask:0xf bank_mask:0xf bound_ctrl:1
	v_fmac_f32_e32 v133, v168, v132
	v_fmac_f32_e32 v133, v62, v172
	v_mul_f32_e32 v132, 0x3d372713, v133
	v_mul_f32_e32 v132, v133, v132
	v_fma_f32 v132, v133, v132, v133
	v_mul_f32_e32 v132, 0xbfcc422a, v132
	v_mul_f32_e32 v132, 0x3fb8aa3b, v132
	v_exp_f32_e32 v132, v132
	v_fmac_f32_e32 v134, v49, v159
	v_mul_f32_e32 v129, v134, v129
	v_add_f32_e32 v132, 1.0, v132
; __device__ __forceinline__ unsigned pk2(float lo, float hi) { unsigned r; asm("v_cvt_pk_bf16_f32 %0, %1, %2" : "=v"(r) : "v"(lo), "v"(hi)); return r; }
; __device__ __forceinline__ float gelu_tanh(float x) { const float y = 1.5957691216f * (x + 0.044715f * x * x * x); return x * __builtin_amdgcn_rcpf(1.0f + __expf(-y)); }
; __device__ __forceinline__ float dpp_shr1(float old, float src) { return __int_as_float(__builtin_amdgcn_update_dpp(__float_as_int(old), __float_as_int(src), 0x111, 0xf, 0xf, false)); }
; __device__ __forceinline__ float dpp_shr2(float old, float src) { return __int_as_float(__builtin_amdgcn_update_dpp(__float_as_int(old), __float_as_int(src), 0x112, 0xf, 0xf, false)); }
; __device__ __forceinline__ float dpp_ror1(float src) { return __int_as_float(__builtin_amdgcn_update_dpp(0, __float_as_int(src), 0x121, 0xf, 0xf, false)); }
; __device__ __forceinline__ float dpp_ror2(float src) { return __int_as_float(__builtin_amdgcn_update_dpp(0, __float_as_int(src), 0x122, 0xf, 0xf, false)); }
;     __device__ __forceinline__ void operator()(const f32x4 (&acc)[2][2][4][2], const Unit& u, int wr, int wc, int fr, int fq) const {
;     ...
;                 for (int m = 0; m < 4; ++m) { const int row = row0 + ai * HALF + m * 16;
;                     const f32x4 g0 = acc[ai][0][m][n], v0 = acc[ai][1][m][n];
;                     f32x4 gp = (f32x4){0.f, 0.f, 0.f, 0.f}, vp = gp;
;                     if (m > 0) { gp = acc[ai][0][m > 0 ? m - 1 : 0][n]; vp = acc[ai][1][m > 0 ? m - 1 : 0][n]; }
;                     f32x4 f;
; #pragma unroll
;                     for (int j = 0; j < 4; ++j) {
;                         const float g1 = dpp_shr1(dpp_ror1(gp[j]), g0[j]), g2 = dpp_shr2(dpp_ror2(gp[j]), g0[j]);
;                         const float v1 = dpp_shr1(dpp_ror1(vp[j]), v0[j]), v2 = dpp_shr2(dpp_ror2(vp[j]), v0[j]);
;                         const float cg_ = bg[j] + g2 * wg0[j] + g1 * wg1[j] + g0[j] * wg2[j];
;                         const float cv_ = bv[j] + v2 * wv0[j] + v1 * wv1[j] + v0[j] * wv2[j];
;                         f[j] = gelu_tanh(cg_) * cv_; }
;                     u32x2 w; w.x = pk2(f[0], f[1]); w.y = pk2(f[2], f[3]);
;                     if (n == 0) res0[ai * 4 + m] = w;
	v_rcp_f32_e32 v132, v132
	v_mov_b32_dpp v135, v50 row_shr:2 row_mask:0xf bank_mask:0xf bound_ctrl:1
	v_fma_f32 v135, v152, v135, v138
	v_mov_b32_dpp v134, v50 row_shr:1 row_mask:0xf bank_mask:0xf bound_ctrl:1
	v_fmac_f32_e32 v135, v156, v134
	v_mul_f32_e32 v132, v133, v132
	v_mov_b32_dpp v134, v63 row_shr:2 row_mask:0xf bank_mask:0xf bound_ctrl:1
	v_fma_f32 v134, v165, v134, v149
	v_mov_b32_dpp v133, v63 row_shr:1 row_mask:0xf bank_mask:0xf bound_ctrl:1
	v_fmac_f32_e32 v134, v169, v133
	v_fmac_f32_e32 v134, v63, v173
	v_mul_f32_e32 v133, 0x3d372713, v134
	v_mul_f32_e32 v133, v134, v133
	v_fma_f32 v133, v134, v133, v134
	v_mul_f32_e32 v133, 0xbfcc422a, v133
	v_mul_f32_e32 v133, 0x3fb8aa3b, v133
	v_exp_f32_e32 v133, v133
	v_fmac_f32_e32 v135, v50, v160
	v_mul_f32_e32 v132, v135, v132
	v_add_f32_e32 v133, 1.0, v133
	v_rcp_f32_e32 v133, v133
	v_mov_b32_dpp v178, v51 row_shr:2 row_mask:0xf bank_mask:0xf bound_ctrl:1
	v_fma_f32 v178, v153, v178, v139
	v_mul_f32_e32 v133, v134, v133
	v_cvt_pk_bf16_f32 v134, v128, v129
	v_mov_b32_dpp v135, v51 row_shr:1 row_mask:0xf bank_mask:0xf bound_ctrl:1
	v_mov_b32_dpp v129, v60 row_ror:2 row_mask:0xf bank_mask:0xf
	v_mov_b32_dpp v128, v60 row_ror:1 row_mask:0xf bank_mask:0xf
	v_fmac_f32_e32 v178, v157, v135
	v_mov_b32_dpp v129, v52 row_shr:2 row_mask:0xf bank_mask:0xf
	v_mov_b32_dpp v128, v52 row_shr:1 row_mask:0xf bank_mask:0xf
	v_fma_f32 v129, v162, v129, v146
	v_fmac_f32_e32 v129, v166, v128
	v_fmac_f32_e32 v129, v52, v170
	v_mul_f32_e32 v128, 0x3d372713, v129
	v_mul_f32_e32 v128, v129, v128
	v_fma_f32 v128, v129, v128, v129
	v_mul_f32_e32 v128, 0xbfcc422a, v128
	v_mul_f32_e32 v128, 0x3fb8aa3b, v128
	v_exp_f32_e32 v128, v128
	v_fmac_f32_e32 v178, v51, v161
	v_mul_f32_e32 v133, v178, v133
	v_cvt_pk_bf16_f32 v135, v132, v133
	v_add_f32_e32 v128, 1.0, v128
	v_mov_b32_dpp v133, v48 row_ror:2 row_mask:0xf bank_mask:0xf
	v_rcp_f32_e32 v128, v128
	v_mov_b32_dpp v132, v48 row_ror:1 row_mask:0xf bank_mask:0xf
	v_mov_b32_dpp v133, v32 row_shr:2 row_mask:0xf bank_mask:0xf
	v_fma_f32 v133, v150, v133, v136
	v_mov_b32_dpp v132, v32 row_shr:1 row_mask:0xf bank_mask:0xf
	v_fmac_f32_e32 v133, v154, v132
	v_mul_f32_e32 v128, v129, v128
	v_mov_b32_dpp v132, v61 row_ror:2 row_mask:0xf bank_mask:0xf
	v_fmac_f32_e32 v133, v32, v158
	v_mov_b32_dpp v129, v61 row_ror:1 row_mask:0xf bank_mask:0xf
	v_mov_b32_dpp v132, v53 row_shr:2 row_mask:0xf bank_mask:0xf
	v_fma_f32 v132, v163, v132, v147
	v_mov_b32_dpp v129, v53 row_shr:1 row_mask:0xf bank_mask:0xf
	v_fmac_f32_e32 v132, v167, v129
	v_fmac_f32_e32 v132, v53, v171
	v_mul_f32_e32 v129, 0x3d372713, v132
	v_mul_f32_e32 v129, v132, v129
	v_fma_f32 v129, v132, v129, v132
	v_mul_f32_e32 v129, 0xbfcc422a, v129
	v_mul_f32_e32 v129, 0x3fb8aa3b, v129
	v_exp_f32_e32 v129, v129
	v_mul_f32_e32 v128, v133, v128
	v_add_f32_e32 v129, 1.0, v129
	v_mov_b32_dpp v178, v49 row_ror:2 row_mask:0xf bank_mask:0xf
	v_rcp_f32_e32 v129, v129
	v_mov_b32_dpp v133, v49 row_ror:1 row_mask:0xf bank_mask:0xf
	v_mov_b32_dpp v178, v33 row_shr:2 row_mask:0xf bank_mask:0xf
	v_fma_f32 v178, v151, v178, v137
	v_mov_b32_dpp v133, v33 row_shr:1 row_mask:0xf bank_mask:0xf
	v_fmac_f32_e32 v178, v155, v133
	v_mul_f32_e32 v129, v132, v129
	v_mov_b32_dpp v133, v62 row_ror:2 row_mask:0xf bank_mask:0xf
	v_fmac_f32_e32 v178, v33, v159
	v_mov_b32_dpp v132, v62 row_ror:1 row_mask:0xf bank_mask:0xf
	v_mov_b32_dpp v133, v54 row_shr:2 row_mask:0xf bank_mask:0xf
	v_fma_f32 v133, v164, v133, v148
	v_mov_b32_dpp v132, v54 row_shr:1 row_mask:0xf bank_mask:0xf
	v_fmac_f32_e32 v133, v168, v132
	v_fmac_f32_e32 v133, v54, v172
	v_mul_f32_e32 v132, 0x3d372713, v133
	v_mul_f32_e32 v132, v133, v132
	v_fma_f32 v132, v133, v132, v133
	v_mul_f32_e32 v132, 0xbfcc422a, v132
	v_mul_f32_e32 v132, 0x3fb8aa3b, v132
	v_exp_f32_e32 v132, v132
	v_mul_f32_e32 v129, v178, v129
	v_fma_f32 v179, v152, v179, v138
	v_add_f32_e32 v132, 1.0, v132
	v_rcp_f32_e32 v132, v132
	v_mov_b32_dpp v178, v50 row_ror:1 row_mask:0xf bank_mask:0xf
	v_fma_f32 v180, v153, v180, v139
	v_cvt_pk_bf16_f32 v128, v128, v129
	v_mul_f32_e32 v132, v133, v132
	v_mov_b32_dpp v178, v34 row_shr:1 row_mask:0xf bank_mask:0xf
	v_fmac_f32_e32 v179, v156, v178
	v_fmac_f32_e32 v179, v34, v160
	v_mov_b32_dpp v178, v63 row_ror:2 row_mask:0xf bank_mask:0xf
	v_mov_b32_dpp v133, v63 row_ror:1 row_mask:0xf bank_mask:0xf
	v_mul_f32_e32 v132, v179, v132
	v_mov_b32_dpp v178, v55 row_shr:2 row_mask:0xf bank_mask:0xf
	v_mov_b32_dpp v133, v55 row_shr:1 row_mask:0xf bank_mask:0xf
	v_fma_f32 v178, v165, v178, v149
	v_fmac_f32_e32 v178, v169, v133
	v_fmac_f32_e32 v178, v55, v173
	v_mul_f32_e32 v133, 0x3d372713, v178
	v_mul_f32_e32 v133, v178, v133
	v_fma_f32 v133, v178, v133, v178
	v_mul_f32_e32 v133, 0xbfcc422a, v133
	v_mul_f32_e32 v133, 0x3fb8aa3b, v133
	v_exp_f32_e32 v133, v133
	v_fma_f32 v181, v152, v181, v138
	v_fma_f32 v184, v153, v184, v139
	v_add_f32_e32 v133, 1.0, v133
	v_rcp_f32_e32 v133, v133
	v_mov_b32_dpp v179, v51 row_ror:1 row_mask:0xf bank_mask:0xf
	v_mul_f32_e32 v133, v178, v133
	s_nop 0
	v_mov_b32_dpp v179, v35 row_shr:1 row_mask:0xf bank_mask:0xf
	v_fmac_f32_e32 v180, v157, v179
	v_fmac_f32_e32 v180, v35, v161
	v_mul_f32_e32 v133, v180, v133
	v_cvt_pk_bf16_f32 v129, v132, v133
	s_nop 0
	v_mov_b32_dpp v133, v52 row_ror:2 row_mask:0xf bank_mask:0xf
	v_mov_b32_dpp v132, v52 row_ror:1 row_mask:0xf bank_mask:0xf
	s_nop 0
	v_mov_b32_dpp v133, v36 row_shr:2 row_mask:0xf bank_mask:0xf
	v_mov_b32_dpp v132, v36 row_shr:1 row_mask:0xf bank_mask:0xf
	v_fma_f32 v133, v162, v133, v146
	v_fmac_f32_e32 v133, v166, v132
	v_fmac_f32_e32 v133, v36, v170
	v_mul_f32_e32 v132, 0x3d372713, v133
; __device__ __forceinline__ unsigned pk2(float lo, float hi) { unsigned r; asm("v_cvt_pk_bf16_f32 %0, %1, %2" : "=v"(r) : "v"(lo), "v"(hi)); return r; }
; __device__ __forceinline__ float gelu_tanh(float x) { const float y = 1.5957691216f * (x + 0.044715f * x * x * x); return x * __builtin_amdgcn_rcpf(1.0f + __expf(-y)); }
; __device__ __forceinline__ float dpp_shr1(float old, float src) { return __int_as_float(__builtin_amdgcn_update_dpp(__float_as_int(old), __float_as_int(src), 0x111, 0xf, 0xf, false)); }
; __device__ __forceinline__ float dpp_shr2(float old, float src) { return __int_as_float(__builtin_amdgcn_update_dpp(__float_as_int(old), __float_as_int(src), 0x112, 0xf, 0xf, false)); }
; __device__ __forceinline__ float dpp_ror1(float src) { return __int_as_float(__builtin_amdgcn_update_dpp(0, __float_as_int(src), 0x121, 0xf, 0xf, false)); }
;     __device__ __forceinline__ void operator()(const f32x4 (&acc)[2][2][4][2], const Unit& u, int wr, int wc, int fr, int fq) const {
;     ...
;                 for (int m = 0; m < 4; ++m) { const int row = row0 + ai * HALF + m * 16;
;                     const f32x4 g0 = acc[ai][0][m][n], v0 = acc[ai][1][m][n];
;                     f32x4 gp = (f32x4){0.f, 0.f, 0.f, 0.f}, vp = gp;
;                     if (m > 0) { gp = acc[ai][0][m > 0 ? m - 1 : 0][n]; vp = acc[ai][1][m > 0 ? m - 1 : 0][n]; }
;                     f32x4 f;
; #pragma unroll
;                     for (int j = 0; j < 4; ++j) {
;                         const float g1 = dpp_shr1(dpp_ror1(gp[j]), g0[j]), g2 = dpp_shr2(dpp_ror2(gp[j]), g0[j]);
;                         const float v1 = dpp_shr1(dpp_ror1(vp[j]), v0[j]), v2 = dpp_shr2(dpp_ror2(vp[j]), v0[j]);
;                         const float cg_ = bg[j] + g2 * wg0[j] + g1 * wg1[j] + g0[j] * wg2[j];
;                         const float cv_ = bv[j] + v2 * wv0[j] + v1 * wv1[j] + v0[j] * wv2[j];
;                         f[j] = gelu_tanh(cg_) * cv_; }
;                     u32x2 w; w.x = pk2(f[0], f[1]); w.y = pk2(f[2], f[3]);
;                     if (n == 0) res0[ai * 4 + m] = w;
;                     else if (m > 0 || fr >= 2) { u32x4 w4; w4.x = res0[ai * 4 + m].x; w4.y = res0[ai * 4 + m].y; w4.z = w.x; w4.w = w.y; *(u32x4*)(F + (size_t)row * DFF + j0) = w4; }
	v_mul_f32_e32 v132, v133, v132
	v_fma_f32 v132, v133, v132, v133
	v_mul_f32_e32 v132, 0xbfcc422a, v132
	v_mul_f32_e32 v132, 0x3fb8aa3b, v132
	v_exp_f32_e32 v132, v132
	v_mov_b32_dpp v179, v32 row_ror:2 row_mask:0xf bank_mask:0xf
	v_mov_b32_dpp v178, v32 row_ror:1 row_mask:0xf bank_mask:0xf
	v_add_f32_e32 v132, 1.0, v132
	v_rcp_f32_e32 v132, v132
	v_mov_b32_dpp v179, v16 row_shr:2 row_mask:0xf bank_mask:0xf
	v_mov_b32_dpp v178, v16 row_shr:1 row_mask:0xf bank_mask:0xf
	v_fma_f32 v179, v150, v179, v136
	v_fmac_f32_e32 v179, v154, v178
	v_mul_f32_e32 v132, v133, v132
	v_mov_b32_dpp v178, v53 row_ror:2 row_mask:0xf bank_mask:0xf
	v_fmac_f32_e32 v179, v16, v158
	v_mov_b32_dpp v133, v53 row_ror:1 row_mask:0xf bank_mask:0xf
	v_mov_b32_dpp v178, v37 row_shr:2 row_mask:0xf bank_mask:0xf
	v_fma_f32 v178, v163, v178, v147
	v_mov_b32_dpp v133, v37 row_shr:1 row_mask:0xf bank_mask:0xf
	v_fmac_f32_e32 v178, v167, v133
	v_fmac_f32_e32 v178, v37, v171
	v_mul_f32_e32 v133, 0x3d372713, v178
	v_mul_f32_e32 v133, v178, v133
	v_fma_f32 v133, v178, v133, v178
	v_mul_f32_e32 v133, 0xbfcc422a, v133
	v_mul_f32_e32 v133, 0x3fb8aa3b, v133
	v_exp_f32_e32 v133, v133
	v_mul_f32_e32 v132, v179, v132
	v_mov_b32_dpp v180, v33 row_ror:2 row_mask:0xf bank_mask:0xf
	v_add_f32_e32 v133, 1.0, v133
	v_rcp_f32_e32 v133, v133
	v_mov_b32_dpp v179, v33 row_ror:1 row_mask:0xf bank_mask:0xf
	v_mov_b32_dpp v180, v17 row_shr:2 row_mask:0xf bank_mask:0xf
	v_fma_f32 v180, v151, v180, v137
	v_mov_b32_dpp v179, v17 row_shr:1 row_mask:0xf bank_mask:0xf
	v_fmac_f32_e32 v180, v155, v179
	v_mul_f32_e32 v133, v178, v133
	v_mov_b32_dpp v179, v54 row_ror:2 row_mask:0xf bank_mask:0xf
	v_fmac_f32_e32 v180, v17, v159
	v_mov_b32_dpp v178, v54 row_ror:1 row_mask:0xf bank_mask:0xf
	v_mov_b32_dpp v179, v38 row_shr:2 row_mask:0xf bank_mask:0xf
	v_fma_f32 v179, v164, v179, v148
	v_mov_b32_dpp v178, v38 row_shr:1 row_mask:0xf bank_mask:0xf
	v_fmac_f32_e32 v179, v168, v178
	v_fmac_f32_e32 v179, v38, v172
	v_mul_f32_e32 v178, 0x3d372713, v179
	v_mul_f32_e32 v178, v179, v178
	v_fma_f32 v178, v179, v178, v179
	v_mul_f32_e32 v178, 0xbfcc422a, v178
	v_mul_f32_e32 v178, 0x3fb8aa3b, v178
	v_exp_f32_e32 v178, v178
	v_mul_f32_e32 v133, v180, v133
	v_cvt_pk_bf16_f32 v132, v132, v133
	v_add_f32_e32 v178, 1.0, v178
	v_rcp_f32_e32 v178, v178
	v_mov_b32_dpp v180, v34 row_ror:1 row_mask:0xf bank_mask:0xf
	v_mul_f32_e32 v178, v179, v178
	s_nop 0
	v_mov_b32_dpp v180, v18 row_shr:1 row_mask:0xf bank_mask:0xf
	v_fmac_f32_e32 v181, v156, v180
	v_fmac_f32_e32 v181, v18, v160
	v_mov_b32_dpp v180, v55 row_ror:2 row_mask:0xf bank_mask:0xf
	v_mov_b32_dpp v179, v55 row_ror:1 row_mask:0xf bank_mask:0xf
	v_mul_f32_e32 v178, v181, v178
	v_mov_b32_dpp v180, v39 row_shr:2 row_mask:0xf bank_mask:0xf
	v_mov_b32_dpp v179, v39 row_shr:1 row_mask:0xf bank_mask:0xf
	v_fma_f32 v180, v165, v180, v149
	v_fmac_f32_e32 v180, v169, v179
	v_fmac_f32_e32 v180, v39, v173
	v_mul_f32_e32 v179, 0x3d372713, v180
	v_mul_f32_e32 v179, v180, v179
	v_fma_f32 v179, v180, v179, v180
	v_mul_f32_e32 v179, 0xbfcc422a, v179
	v_mul_f32_e32 v179, 0x3fb8aa3b, v179
	v_exp_f32_e32 v179, v179
	s_nop 0
	v_add_f32_e32 v179, 1.0, v179
	v_rcp_f32_e32 v179, v179
	v_mov_b32_dpp v181, v35 row_ror:1 row_mask:0xf bank_mask:0xf
	v_mul_f32_e32 v179, v180, v179
	s_nop 0
	v_mov_b32_dpp v181, v19 row_shr:1 row_mask:0xf bank_mask:0xf
	v_fmac_f32_e32 v184, v157, v181
	v_fmac_f32_e32 v184, v19, v161
	v_mul_f32_e32 v179, v184, v179
	v_cvt_pk_bf16_f32 v133, v178, v179
	s_nop 0
	v_mov_b32_dpp v179, v36 row_ror:2 row_mask:0xf bank_mask:0xf
	v_mov_b32_dpp v178, v36 row_ror:1 row_mask:0xf bank_mask:0xf
	v_mov_b32_dpp v180, v16 row_ror:1 row_mask:0xf bank_mask:0xf
	v_mov_b32_dpp v179, v20 row_shr:2 row_mask:0xf bank_mask:0xf
	v_mov_b32_dpp v178, v20 row_shr:1 row_mask:0xf bank_mask:0xf
	v_fma_f32 v146, v162, v179, v146
	v_fmac_f32_e32 v146, v166, v178
	v_fmac_f32_e32 v146, v20, v170
	v_mul_f32_e32 v162, 0x3d372713, v146
	v_mul_f32_e32 v162, v146, v162
	v_fma_f32 v162, v146, v162, v146
	v_mul_f32_e32 v162, 0xbfcc422a, v162
	v_mul_f32_e32 v162, 0x3fb8aa3b, v162
	v_exp_f32_e32 v162, v162
	v_mov_b32_dpp v180, v4 row_shr:1 row_mask:0xf bank_mask:0xf
	v_add_f32_e32 v162, 1.0, v162
	v_mov_b32_dpp v166, v16 row_ror:2 row_mask:0xf bank_mask:0xf
	v_rcp_f32_e32 v162, v162
	s_nop 0
	v_mov_b32_dpp v166, v4 row_shr:2 row_mask:0xf bank_mask:0xf
	v_fma_f32 v136, v150, v166, v136
	v_fmac_f32_e32 v136, v154, v180
	v_fmac_f32_e32 v136, v4, v158
	v_mul_f32_e32 v146, v146, v162
	v_mul_f32_e32 v150, v136, v146
	global_load_dwordx4 v[178:181], v[176:177], off offset:16
	v_mov_b32_dpp v146, v37 row_ror:2 row_mask:0xf bank_mask:0xf
	v_mov_b32_dpp v136, v37 row_ror:1 row_mask:0xf bank_mask:0xf
	s_nop 0
	v_mov_b32_dpp v146, v21 row_shr:2 row_mask:0xf bank_mask:0xf
	v_mov_b32_dpp v136, v21 row_shr:1 row_mask:0xf bank_mask:0xf
	v_fma_f32 v186, v163, v146, v147
	v_fmac_f32_e32 v186, v167, v136
	v_or_b32_e32 v146, 4, v130
	v_fmac_f32_e32 v186, v21, v171
	v_ashrrev_i32_e32 v147, 31, v146
	v_mul_f32_e32 v136, 0x3d372713, v186
	v_lshlrev_b64 v[146:147], 2, v[146:147]
	v_mul_f32_e32 v136, v186, v136
	v_lshl_add_u64 v[170:171], s[60:61], 0, v[146:147]
	v_fma_f32 v136, v186, v136, v186
	v_lshl_add_u64 v[162:163], s[56:57], 0, v[146:147]
	v_lshl_add_u64 v[166:167], s[58:59], 0, v[146:147]
	global_load_dwordx4 v[198:201], v[170:171], off
	global_load_dwordx4 v[206:209], v[182:183], off offset:16
	s_nop 0
	global_load_dwordx4 v[182:185], v[162:163], off
	global_load_dwordx4 v[202:205], v[166:167], off
	v_mul_f32_e32 v136, 0xbfcc422a, v136
	v_mul_f32_e32 v136, 0x3fb8aa3b, v136
	v_exp_f32_e32 v136, v136
; __device__ __forceinline__ unsigned pk2(float lo, float hi) { unsigned r; asm("v_cvt_pk_bf16_f32 %0, %1, %2" : "=v"(r) : "v"(lo), "v"(hi)); return r; }
; __device__ __forceinline__ float gelu_tanh(float x) { const float y = 1.5957691216f * (x + 0.044715f * x * x * x); return x * __builtin_amdgcn_rcpf(1.0f + __expf(-y)); }
; __device__ __forceinline__ float dpp_shr1(float old, float src) { return __int_as_float(__builtin_amdgcn_update_dpp(__float_as_int(old), __float_as_int(src), 0x111, 0xf, 0xf, false)); }
; __device__ __forceinline__ float dpp_shr2(float old, float src) { return __int_as_float(__builtin_amdgcn_update_dpp(__float_as_int(old), __float_as_int(src), 0x112, 0xf, 0xf, false)); }
; __device__ __forceinline__ float dpp_ror1(float src) { return __int_as_float(__builtin_amdgcn_update_dpp(0, __float_as_int(src), 0x121, 0xf, 0xf, false)); }
;     __device__ __forceinline__ void operator()(const f32x4 (&acc)[2][2][4][2], const Unit& u, int wr, int wc, int fr, int fq) const {
;     ...
;                 for (int m = 0; m < 4; ++m) { const int row = row0 + ai * HALF + m * 16;
;                     const f32x4 g0 = acc[ai][0][m][n], v0 = acc[ai][1][m][n];
;                     f32x4 gp = (f32x4){0.f, 0.f, 0.f, 0.f}, vp = gp;
;                     if (m > 0) { gp = acc[ai][0][m > 0 ? m - 1 : 0][n]; vp = acc[ai][1][m > 0 ? m - 1 : 0][n]; }
;                     f32x4 f;
; #pragma unroll
;                     for (int j = 0; j < 4; ++j) {
;                         const float g1 = dpp_shr1(dpp_ror1(gp[j]), g0[j]), g2 = dpp_shr2(dpp_ror2(gp[j]), g0[j]);
;                         const float v1 = dpp_shr1(dpp_ror1(vp[j]), v0[j]), v2 = dpp_shr2(dpp_ror2(vp[j]), v0[j]);
;                         const float cg_ = bg[j] + g2 * wg0[j] + g1 * wg1[j] + g0[j] * wg2[j];
;                         const float cv_ = bv[j] + v2 * wv0[j] + v1 * wv1[j] + v0[j] * wv2[j];
;                         f[j] = gelu_tanh(cg_) * cv_; }
;                     u32x2 w; w.x = pk2(f[0], f[1]); w.y = pk2(f[2], f[3]);
;                     if (n == 0) res0[ai * 4 + m] = w;
;                     else if (m > 0 || fr >= 2) { u32x4 w4; w4.x = res0[ai * 4 + m].x; w4.y = res0[ai * 4 + m].y; w4.z = w.x; w4.w = w.y; *(u32x4*)(F + (size_t)row * DFF + j0) = w4; }
	v_mov_b32_dpp v158, v17 row_ror:2 row_mask:0xf bank_mask:0xf
	v_add_f32_e32 v136, 1.0, v136
	v_rcp_f32_e32 v136, v136
	v_mov_b32_dpp v154, v17 row_ror:1 row_mask:0xf bank_mask:0xf
	v_mov_b32_dpp v158, v5 row_shr:2 row_mask:0xf bank_mask:0xf
	v_fma_f32 v151, v151, v158, v137
	v_mov_b32_dpp v154, v5 row_shr:1 row_mask:0xf bank_mask:0xf
	v_fmac_f32_e32 v151, v155, v154
	v_mul_f32_e32 v154, v186, v136
	v_lshl_add_u64 v[136:137], s[46:47], 0, v[146:147]
	global_load_dwordx4 v[186:189], v[136:137], off
	v_lshl_add_u64 v[136:137], s[48:49], 0, v[146:147]
	v_lshl_add_u64 v[146:147], s[54:55], 0, v[146:147]
	global_load_dwordx4 v[190:193], v[136:137], off
	global_load_dwordx4 v[194:197], v[146:147], off
	v_mov_b32_dpp v146, v38 row_ror:2 row_mask:0xf bank_mask:0xf
	v_mov_b32_dpp v137, v38 row_ror:1 row_mask:0xf bank_mask:0xf
	v_mov_b32_dpp v147, v18 row_ror:1 row_mask:0xf bank_mask:0xf
	v_mov_b32_dpp v146, v22 row_shr:2 row_mask:0xf bank_mask:0xf
	v_mov_b32_dpp v137, v22 row_shr:1 row_mask:0xf bank_mask:0xf
	v_fma_f32 v146, v164, v146, v148
	v_fmac_f32_e32 v146, v168, v137
	v_fmac_f32_e32 v146, v22, v172
	v_mul_f32_e32 v137, 0x3d372713, v146
	v_mul_f32_e32 v137, v146, v137
	v_fma_f32 v137, v146, v137, v146
	v_mul_f32_e32 v137, 0xbfcc422a, v137
	v_mul_f32_e32 v137, 0x3fb8aa3b, v137
	v_exp_f32_e32 v137, v137
	v_mov_b32_dpp v147, v6 row_shr:1 row_mask:0xf bank_mask:0xf
	v_fmac_f32_e32 v151, v5, v159
	v_add_f32_e32 v137, 1.0, v137
	v_mov_b32_dpp v148, v18 row_ror:2 row_mask:0xf bank_mask:0xf
	v_rcp_f32_e32 v137, v137
	v_mul_f32_e32 v136, v151, v154
	v_mov_b32_dpp v148, v6 row_shr:2 row_mask:0xf bank_mask:0xf
	v_fma_f32 v138, v152, v148, v138
	v_fmac_f32_e32 v138, v156, v147
	v_fmac_f32_e32 v138, v6, v160
	v_mul_f32_e32 v137, v146, v137
	v_mul_f32_e32 v137, v138, v137
	v_mov_b32_dpp v146, v39 row_ror:2 row_mask:0xf bank_mask:0xf
	v_mov_b32_dpp v138, v39 row_ror:1 row_mask:0xf bank_mask:0xf
	s_nop 0
	v_mov_b32_dpp v146, v23 row_shr:2 row_mask:0xf bank_mask:0xf
	v_fmac_f32_e32 v149, v165, v146
	v_mov_b32_dpp v138, v23 row_shr:1 row_mask:0xf bank_mask:0xf
	v_fmac_f32_e32 v149, v169, v138
	v_fmac_f32_e32 v149, v23, v173
	v_mul_f32_e32 v138, 0x3d372713, v149
	v_mul_f32_e32 v138, v149, v138
	v_fma_f32 v138, v149, v138, v149
	v_mul_f32_e32 v138, 0xbfcc422a, v138
	v_mul_f32_e32 v138, 0x3fb8aa3b, v138
	v_exp_f32_e32 v138, v138
	v_mov_b32_dpp v147, v19 row_ror:1 row_mask:0xf bank_mask:0xf
	v_add_f32_e32 v138, 1.0, v138
	v_mov_b32_dpp v146, v19 row_ror:2 row_mask:0xf bank_mask:0xf
	v_rcp_f32_e32 v138, v138
	v_mov_b32_dpp v147, v7 row_shr:1 row_mask:0xf bank_mask:0xf
	v_mov_b32_dpp v146, v7 row_shr:2 row_mask:0xf bank_mask:0xf
	v_fmac_f32_e32 v139, v153, v146
	v_fmac_f32_e32 v139, v157, v147
	v_fmac_f32_e32 v139, v7, v161
	v_mul_f32_e32 v138, v149, v138
	v_mul_f32_e32 v139, v139, v138
	v_cvt_pk_bf16_f32 v139, v137, v139
	v_cvt_pk_bf16_f32 v138, v150, v136
	v_mov_b32_dpp v137, v120 row_shr:2 row_mask:0xf bank_mask:0xf bound_ctrl:1
	v_mov_b32_dpp v136, v120 row_shr:1 row_mask:0xf bank_mask:0xf bound_ctrl:1
	s_waitcnt vmcnt(0)
	v_fma_f32 v137, v206, v137, v178
	v_fmac_f32_e32 v137, v198, v136
	v_fmac_f32_e32 v137, v120, v202
	v_mul_f32_e32 v136, 0x3d372713, v137
	v_mul_f32_e32 v136, v137, v136
	v_fma_f32 v136, v137, v136, v137
	v_mul_f32_e32 v136, 0xbfcc422a, v136
	v_mul_f32_e32 v136, 0x3fb8aa3b, v136
	v_exp_f32_e32 v136, v136
	v_mov_b32_dpp v147, v104 row_shr:2 row_mask:0xf bank_mask:0xf bound_ctrl:1
	v_fma_f32 v147, v182, v147, v186
	v_add_f32_e32 v136, 1.0, v136
	v_rcp_f32_e32 v136, v136
	v_mov_b32_dpp v146, v104 row_shr:1 row_mask:0xf bank_mask:0xf bound_ctrl:1
	v_fmac_f32_e32 v147, v194, v146
	v_mul_f32_e32 v136, v137, v136
	v_mov_b32_dpp v146, v121 row_shr:2 row_mask:0xf bank_mask:0xf bound_ctrl:1
	v_fma_f32 v146, v207, v146, v179
	v_mov_b32_dpp v137, v121 row_shr:1 row_mask:0xf bank_mask:0xf bound_ctrl:1
	v_fmac_f32_e32 v146, v199, v137
	v_fmac_f32_e32 v146, v121, v203
	v_mul_f32_e32 v137, 0x3d372713, v146
	v_mul_f32_e32 v137, v146, v137
	v_fma_f32 v137, v146, v137, v146
	v_mul_f32_e32 v137, 0xbfcc422a, v137
	v_mul_f32_e32 v137, 0x3fb8aa3b, v137
	v_exp_f32_e32 v137, v137
	v_fmac_f32_e32 v147, v104, v190
	v_mul_f32_e32 v136, v147, v136
	v_add_f32_e32 v137, 1.0, v137
	v_rcp_f32_e32 v137, v137
	v_mov_b32_dpp v148, v105 row_shr:2 row_mask:0xf bank_mask:0xf bound_ctrl:1
	v_mov_b32_dpp v147, v105 row_shr:1 row_mask:0xf bank_mask:0xf bound_ctrl:1
	v_fma_f32 v148, v183, v148, v187
	v_fmac_f32_e32 v148, v195, v147
	v_mul_f32_e32 v137, v146, v137
	v_mov_b32_dpp v147, v122 row_shr:2 row_mask:0xf bank_mask:0xf bound_ctrl:1
	v_fma_f32 v147, v208, v147, v180
	v_mov_b32_dpp v146, v122 row_shr:1 row_mask:0xf bank_mask:0xf bound_ctrl:1
	v_fmac_f32_e32 v147, v200, v146
	v_fmac_f32_e32 v147, v122, v204
	v_mul_f32_e32 v146, 0x3d372713, v147
	v_mul_f32_e32 v146, v147, v146
	v_fma_f32 v146, v147, v146, v147
	v_mul_f32_e32 v146, 0xbfcc422a, v146
	v_mul_f32_e32 v146, 0x3fb8aa3b, v146
	v_exp_f32_e32 v146, v146
	v_fmac_f32_e32 v148, v105, v191
	v_mul_f32_e32 v137, v148, v137
	v_add_f32_e32 v146, 1.0, v146
	v_rcp_f32_e32 v146, v146
	v_mov_b32_dpp v149, v106 row_shr:2 row_mask:0xf bank_mask:0xf bound_ctrl:1
	v_fma_f32 v149, v184, v149, v188
	v_mov_b32_dpp v148, v106 row_shr:1 row_mask:0xf bank_mask:0xf bound_ctrl:1
	v_fmac_f32_e32 v149, v196, v148
	v_mul_f32_e32 v146, v147, v146
	v_mov_b32_dpp v148, v123 row_shr:2 row_mask:0xf bank_mask:0xf bound_ctrl:1
	v_fma_f32 v148, v209, v148, v181
	v_mov_b32_dpp v147, v123 row_shr:1 row_mask:0xf bank_mask:0xf bound_ctrl:1
	v_fmac_f32_e32 v148, v201, v147
	v_fmac_f32_e32 v148, v123, v205
	v_mul_f32_e32 v147, 0x3d372713, v148
	v_mul_f32_e32 v147, v148, v147
	v_fma_f32 v147, v148, v147, v148
	v_mul_f32_e32 v147, 0xbfcc422a, v147
	v_mul_f32_e32 v147, 0x3fb8aa3b, v147
	v_exp_f32_e32 v147, v147
	v_fmac_f32_e32 v149, v106, v192
	v_mov_b32_dpp v242, v107 row_shr:2 row_mask:0xf bank_mask:0xf
	v_mul_f32_e32 v146, v149, v146
	v_add_f32_e32 v147, 1.0, v147
	v_rcp_f32_e32 v147, v147
	v_mov_b32_dpp v241, v107 row_shr:1 row_mask:0xf bank_mask:0xf
	v_fma_f32 v149, v185, v242, v189
	v_fmac_f32_e32 v149, v197, v241
	v_fmac_f32_e32 v149, v107, v193
	v_mul_f32_e32 v147, v148, v147
	v_mul_f32_e32 v147, v149, v147
	v_cvt_pk_bf16_f32 v176, v136, v137
	v_cvt_pk_bf16_f32 v177, v146, v147
	s_and_saveexec_b64 s[0:1], s[8:9]
	s_cbranch_execz .LBB0_1204
	v_mov_b64_e32 v[136:137], s[40:41]
	v_mad_i64_i32 v[136:137], s[42:43], v248, s4, v[136:137]
	v_lshl_add_u64 v[136:137], v[130:131], 1, v[136:137]
	global_store_dwordx4 v[136:137], v[174:177], off

; __device__ __forceinline__ unsigned pk2(float lo, float hi) { unsigned r; asm("v_cvt_pk_bf16_f32 %0, %1, %2" : "=v"(r) : "v"(lo), "v"(hi)); return r; }
; __device__ __forceinline__ float gelu_tanh(float x) { const float y = 1.5957691216f * (x + 0.044715f * x * x * x); return x * __builtin_amdgcn_rcpf(1.0f + __expf(-y)); }
; __device__ __forceinline__ float dpp_shr1(float old, float src) { return __int_as_float(__builtin_amdgcn_update_dpp(__float_as_int(old), __float_as_int(src), 0x111, 0xf, 0xf, false)); }
; __device__ __forceinline__ float dpp_shr2(float old, float src) { return __int_as_float(__builtin_amdgcn_update_dpp(__float_as_int(old), __float_as_int(src), 0x112, 0xf, 0xf, false)); }
; __device__ __forceinline__ float dpp_ror1(float src) { return __int_as_float(__builtin_amdgcn_update_dpp(0, __float_as_int(src), 0x121, 0xf, 0xf, false)); }
;     __device__ __forceinline__ void operator()(const f32x4 (&acc)[2][2][4][2], const Unit& u, int wr, int wc, int fr, int fq) const {
;     ...
;                 for (int m = 0; m < 4; ++m) { const int row = row0 + ai * HALF + m * 16;
;                     const f32x4 g0 = acc[ai][0][m][n], v0 = acc[ai][1][m][n];
;                     f32x4 gp = (f32x4){0.f, 0.f, 0.f, 0.f}, vp = gp;
;                     if (m > 0) { gp = acc[ai][0][m > 0 ? m - 1 : 0][n]; vp = acc[ai][1][m > 0 ? m - 1 : 0][n]; }
;                     f32x4 f;
; #pragma unroll
;                     for (int j = 0; j < 4; ++j) {
;                         const float g1 = dpp_shr1(dpp_ror1(gp[j]), g0[j]), g2 = dpp_shr2(dpp_ror2(gp[j]), g0[j]);
;                         const float v1 = dpp_shr1(dpp_ror1(vp[j]), v0[j]), v2 = dpp_shr2(dpp_ror2(vp[j]), v0[j]);
;                         const float cg_ = bg[j] + g2 * wg0[j] + g1 * wg1[j] + g0[j] * wg2[j];
;                         const float cv_ = bv[j] + v2 * wv0[j] + v1 * wv1[j] + v0[j] * wv2[j];
;                         f[j] = gelu_tanh(cg_) * cv_; }
;                     u32x2 w; w.x = pk2(f[0], f[1]); w.y = pk2(f[2], f[3]);
;                     if (n == 0) res0[ai * 4 + m] = w;
;                     else if (m > 0 || fr >= 2) { u32x4 w4; w4.x = res0[ai * 4 + m].x; w4.y = res0[ai * 4 + m].y; w4.z = w.x; w4.w = w.y; *(u32x4*)(F + (size_t)row * DFF + j0) = w4; }
.LBB0_1206:
	s_or_b64 exec, exec, s[0:1]
	v_mov_b32_dpp v147, v120 row_ror:2 row_mask:0xf bank_mask:0xf
	v_mov_b32_dpp v146, v104 row_ror:2 row_mask:0xf bank_mask:0xf
	v_mov_b32_dpp v137, v120 row_ror:1 row_mask:0xf bank_mask:0xf
	v_mov_b32_dpp v147, v108 row_shr:2 row_mask:0xf bank_mask:0xf
	v_mov_b32_dpp v136, v104 row_ror:1 row_mask:0xf bank_mask:0xf
	v_mov_b32_dpp v146, v88 row_shr:2 row_mask:0xf bank_mask:0xf
	v_mov_b32_e32 v148, v182
	v_mov_b32_e32 v149, v206
	v_mov_b32_e32 v150, v186
	v_mov_b32_e32 v151, v178
	v_mov_b32_dpp v137, v108 row_shr:1 row_mask:0xf bank_mask:0xf
	v_mov_b32_dpp v136, v88 row_shr:1 row_mask:0xf bank_mask:0xf
	v_pk_fma_f32 v[146:147], v[148:149], v[146:147], v[150:151]
	v_mov_b32_e32 v152, v194
	v_mov_b32_e32 v153, v198
	v_pk_fma_f32 v[136:137], v[152:153], v[136:137], v[146:147]
	v_mov_b32_e32 v146, v88
	v_mov_b32_e32 v147, v108
	v_mov_b32_e32 v154, v190
	v_mov_b32_e32 v155, v202
	v_pk_fma_f32 v[136:137], v[146:147], v[154:155], v[136:137]
	v_mul_f32_e32 v146, 0x3d372713, v137
	v_mul_f32_e32 v146, v137, v146
	v_fma_f32 v146, v137, v146, v137
	v_mul_f32_e32 v146, 0xbfcc422a, v146
	v_mul_f32_e32 v146, 0x3fb8aa3b, v146
	v_exp_f32_e32 v146, v146
	v_mov_b32_dpp v147, v121 row_ror:2 row_mask:0xf bank_mask:0xf
	v_mov_b32_e32 v156, v183
	v_mov_b32_e32 v157, v207
	v_add_f32_e32 v146, 1.0, v146
	v_rcp_f32_e32 v146, v146
	v_mov_b32_dpp v147, v109 row_shr:2 row_mask:0xf bank_mask:0xf
	v_mov_b32_e32 v158, v187
	v_mov_b32_e32 v159, v179
	v_mul_f32_e32 v137, v137, v146
	v_mul_f32_e32 v245, v136, v137
	v_mov_b32_dpp v146, v105 row_ror:2 row_mask:0xf bank_mask:0xf
	v_mov_b32_dpp v137, v121 row_ror:1 row_mask:0xf bank_mask:0xf
	v_mov_b32_dpp v136, v105 row_ror:1 row_mask:0xf bank_mask:0xf
	v_mov_b32_dpp v146, v89 row_shr:2 row_mask:0xf bank_mask:0xf
	v_mov_b32_dpp v137, v109 row_shr:1 row_mask:0xf bank_mask:0xf
	v_mov_b32_dpp v136, v89 row_shr:1 row_mask:0xf bank_mask:0xf
	v_pk_fma_f32 v[146:147], v[156:157], v[146:147], v[158:159]
	v_mov_b32_e32 v160, v195
	v_mov_b32_e32 v161, v199
	v_pk_fma_f32 v[136:137], v[160:161], v[136:137], v[146:147]
	v_mov_b32_e32 v146, v89
	v_mov_b32_e32 v147, v109
	v_mov_b32_e32 v162, v191
	v_mov_b32_e32 v163, v203
	v_pk_fma_f32 v[136:137], v[146:147], v[162:163], v[136:137]
	v_mul_f32_e32 v146, 0x3d372713, v137
	v_mul_f32_e32 v146, v137, v146
	v_fma_f32 v146, v137, v146, v137
	v_mul_f32_e32 v146, 0xbfcc422a, v146
	v_mul_f32_e32 v146, 0x3fb8aa3b, v146
	v_exp_f32_e32 v146, v146
	v_mov_b32_dpp v147, v122 row_ror:2 row_mask:0xf bank_mask:0xf
	v_mov_b32_e32 v164, v184
	v_mov_b32_e32 v165, v208
	v_add_f32_e32 v146, 1.0, v146
	v_rcp_f32_e32 v146, v146
	v_mov_b32_dpp v147, v110 row_shr:2 row_mask:0xf bank_mask:0xf
	v_mov_b32_e32 v166, v188
	v_mov_b32_e32 v167, v180
	v_mul_f32_e32 v137, v137, v146
	v_mul_f32_e32 v251, v136, v137
	v_mov_b32_dpp v146, v106 row_ror:2 row_mask:0xf bank_mask:0xf
	v_mov_b32_dpp v137, v122 row_ror:1 row_mask:0xf bank_mask:0xf
	v_mov_b32_dpp v136, v106 row_ror:1 row_mask:0xf bank_mask:0xf
	v_mov_b32_dpp v146, v90 row_shr:2 row_mask:0xf bank_mask:0xf
	v_mov_b32_dpp v137, v110 row_shr:1 row_mask:0xf bank_mask:0xf
	v_mov_b32_dpp v136, v90 row_shr:1 row_mask:0xf bank_mask:0xf
	v_pk_fma_f32 v[146:147], v[164:165], v[146:147], v[166:167]
	v_mov_b32_e32 v168, v196
	v_mov_b32_e32 v169, v200
	v_pk_fma_f32 v[136:137], v[168:169], v[136:137], v[146:147]
	v_mov_b32_e32 v146, v90
	v_mov_b32_e32 v147, v110
	v_mov_b32_e32 v170, v192
	v_mov_b32_e32 v171, v204
	v_pk_fma_f32 v[136:137], v[146:147], v[170:171], v[136:137]
	v_mul_f32_e32 v146, 0x3d372713, v137
	v_mul_f32_e32 v146, v137, v146
	v_fma_f32 v146, v137, v146, v137
	v_mul_f32_e32 v146, 0xbfcc422a, v146
	v_mul_f32_e32 v146, 0x3fb8aa3b, v146
	v_exp_f32_e32 v146, v146
	v_mov_b32_dpp v147, v123 row_ror:2 row_mask:0xf bank_mask:0xf
	v_mov_b32_e32 v172, v185
	v_mov_b32_e32 v173, v209
	v_add_f32_e32 v146, 1.0, v146
	v_rcp_f32_e32 v146, v146
	v_mov_b32_dpp v147, v111 row_shr:2 row_mask:0xf bank_mask:0xf
	v_mov_b32_e32 v174, v189
	v_mov_b32_e32 v175, v181
	v_mul_f32_e32 v137, v137, v146
	v_mul_f32_e32 v252, v136, v137
	v_mov_b32_dpp v146, v107 row_ror:2 row_mask:0xf bank_mask:0xf
	v_mov_b32_dpp v137, v123 row_ror:1 row_mask:0xf bank_mask:0xf
	v_mov_b32_dpp v136, v107 row_ror:1 row_mask:0xf bank_mask:0xf
	v_mov_b32_dpp v146, v91 row_shr:2 row_mask:0xf bank_mask:0xf
	v_mov_b32_dpp v137, v111 row_shr:1 row_mask:0xf bank_mask:0xf
	v_mov_b32_dpp v136, v91 row_shr:1 row_mask:0xf bank_mask:0xf
	v_pk_fma_f32 v[146:147], v[172:173], v[146:147], v[174:175]
	v_mov_b32_e32 v176, v197
	v_mov_b32_e32 v177, v201
	v_pk_fma_f32 v[136:137], v[176:177], v[136:137], v[146:147]
	v_mov_b32_e32 v146, v91
	v_mov_b32_e32 v147, v111
	v_mov_b32_e32 v242, v193
	v_mov_b32_e32 v243, v205
	v_pk_fma_f32 v[136:137], v[146:147], v[242:243], v[136:137]
	v_or_b32_e32 v244, 16, v248
	v_mul_f32_e32 v146, 0x3d372713, v137
	v_mul_f32_e32 v146, v137, v146
	v_fma_f32 v146, v137, v146, v137
	v_mul_f32_e32 v146, 0xbfcc422a, v146
	v_mul_f32_e32 v146, 0x3fb8aa3b, v146
	v_exp_f32_e32 v146, v146
	v_or_b32_e32 v250, 32, v248
	v_or_b32_e32 v249, 48, v248
	v_add_f32_e32 v146, 1.0, v146
	v_rcp_f32_e32 v146, v146
	s_nop 0
	v_mul_f32_e32 v137, v137, v146
	v_mul_f32_e32 v136, v136, v137
	v_cvt_pk_bf16_f32 v147, v252, v136
	v_mov_b64_e32 v[136:137], s[40:41]
	v_cvt_pk_bf16_f32 v146, v245, v251
	v_mad_i64_i32 v[252:253], s[0:1], v244, s4, v[136:137]
	v_lshlrev_b64 v[244:245], 1, v[130:131]
	v_lshl_add_u64 v[252:253], v[252:253], 0, v[244:245]
	global_store_dwordx4 v[252:253], v[144:147], off
	s_nop 1
	s_nop 0
	v_mov_b32_dpp v147, v108 row_ror:2 row_mask:0xf bank_mask:0xf
; __device__ __forceinline__ unsigned pk2(float lo, float hi) { unsigned r; asm("v_cvt_pk_bf16_f32 %0, %1, %2" : "=v"(r) : "v"(lo), "v"(hi)); return r; }
; __device__ __forceinline__ float gelu_tanh(float x) { const float y = 1.5957691216f * (x + 0.044715f * x * x * x); return x * __builtin_amdgcn_rcpf(1.0f + __expf(-y)); }
; __device__ __forceinline__ float dpp_shr1(float old, float src) { return __int_as_float(__builtin_amdgcn_update_dpp(__float_as_int(old), __float_as_int(src), 0x111, 0xf, 0xf, false)); }
; __device__ __forceinline__ float dpp_shr2(float old, float src) { return __int_as_float(__builtin_amdgcn_update_dpp(__float_as_int(old), __float_as_int(src), 0x112, 0xf, 0xf, false)); }
; __device__ __forceinline__ float dpp_ror1(float src) { return __int_as_float(__builtin_amdgcn_update_dpp(0, __float_as_int(src), 0x121, 0xf, 0xf, false)); }
;     __device__ __forceinline__ void operator()(const f32x4 (&acc)[2][2][4][2], const Unit& u, int wr, int wc, int fr, int fq) const {
;     ...
;                 for (int m = 0; m < 4; ++m) { const int row = row0 + ai * HALF + m * 16;
;                     const f32x4 g0 = acc[ai][0][m][n], v0 = acc[ai][1][m][n];
;                     f32x4 gp = (f32x4){0.f, 0.f, 0.f, 0.f}, vp = gp;
;                     if (m > 0) { gp = acc[ai][0][m > 0 ? m - 1 : 0][n]; vp = acc[ai][1][m > 0 ? m - 1 : 0][n]; }
;                     f32x4 f;
; #pragma unroll
;                     for (int j = 0; j < 4; ++j) {
;                         const float g1 = dpp_shr1(dpp_ror1(gp[j]), g0[j]), g2 = dpp_shr2(dpp_ror2(gp[j]), g0[j]);
;                         const float v1 = dpp_shr1(dpp_ror1(vp[j]), v0[j]), v2 = dpp_shr2(dpp_ror2(vp[j]), v0[j]);
;                         const float cg_ = bg[j] + g2 * wg0[j] + g1 * wg1[j] + g0[j] * wg2[j];
;                         const float cv_ = bv[j] + v2 * wv0[j] + v1 * wv1[j] + v0[j] * wv2[j];
;                         f[j] = gelu_tanh(cg_) * cv_; }
;                     u32x2 w; w.x = pk2(f[0], f[1]); w.y = pk2(f[2], f[3]);
;                     if (n == 0) res0[ai * 4 + m] = w;
;                     else if (m > 0 || fr >= 2) { u32x4 w4; w4.x = res0[ai * 4 + m].x; w4.y = res0[ai * 4 + m].y; w4.z = w.x; w4.w = w.y; *(u32x4*)(F + (size_t)row * DFF + j0) = w4; }
	v_mov_b32_dpp v146, v88 row_ror:2 row_mask:0xf bank_mask:0xf
	v_mov_b32_dpp v145, v108 row_ror:1 row_mask:0xf bank_mask:0xf
	v_mov_b32_dpp v147, v92 row_shr:2 row_mask:0xf bank_mask:0xf
	v_mov_b32_dpp v144, v88 row_ror:1 row_mask:0xf bank_mask:0xf
	v_mov_b32_dpp v146, v72 row_shr:2 row_mask:0xf bank_mask:0xf
	v_mov_b32_dpp v145, v92 row_shr:1 row_mask:0xf bank_mask:0xf
	v_mov_b32_dpp v144, v72 row_shr:1 row_mask:0xf bank_mask:0xf
	v_pk_fma_f32 v[146:147], v[148:149], v[146:147], v[150:151]
	s_nop 0
	v_pk_fma_f32 v[144:145], v[152:153], v[144:145], v[146:147]
	v_mov_b32_e32 v146, v72
	v_mov_b32_e32 v147, v92
	v_pk_fma_f32 v[144:145], v[146:147], v[154:155], v[144:145]
	v_mul_f32_e32 v146, 0x3d372713, v145
	v_mul_f32_e32 v146, v145, v146
	v_fma_f32 v146, v145, v146, v145
	v_mul_f32_e32 v146, 0xbfcc422a, v146
	v_mul_f32_e32 v146, 0x3fb8aa3b, v146
	v_exp_f32_e32 v146, v146
	v_mov_b32_dpp v147, v109 row_ror:2 row_mask:0xf bank_mask:0xf
	v_add_f32_e32 v146, 1.0, v146
	v_rcp_f32_e32 v146, v146
	v_mov_b32_dpp v147, v93 row_shr:2 row_mask:0xf bank_mask:0xf
	v_mul_f32_e32 v145, v145, v146
	v_mul_f32_e32 v251, v144, v145
	v_mov_b32_dpp v146, v89 row_ror:2 row_mask:0xf bank_mask:0xf
	v_mov_b32_dpp v145, v109 row_ror:1 row_mask:0xf bank_mask:0xf
	v_mov_b32_dpp v144, v89 row_ror:1 row_mask:0xf bank_mask:0xf
	v_mov_b32_dpp v146, v73 row_shr:2 row_mask:0xf bank_mask:0xf
	v_mov_b32_dpp v145, v93 row_shr:1 row_mask:0xf bank_mask:0xf
	v_mov_b32_dpp v144, v73 row_shr:1 row_mask:0xf bank_mask:0xf
	v_pk_fma_f32 v[146:147], v[156:157], v[146:147], v[158:159]
	s_nop 0
	v_pk_fma_f32 v[144:145], v[160:161], v[144:145], v[146:147]
	v_mov_b32_e32 v146, v73
	v_mov_b32_e32 v147, v93
	v_pk_fma_f32 v[144:145], v[146:147], v[162:163], v[144:145]
	v_mul_f32_e32 v146, 0x3d372713, v145
	v_mul_f32_e32 v146, v145, v146
	v_fma_f32 v146, v145, v146, v145
	v_mul_f32_e32 v146, 0xbfcc422a, v146
	v_mul_f32_e32 v146, 0x3fb8aa3b, v146
	v_exp_f32_e32 v146, v146
	v_mov_b32_dpp v147, v110 row_ror:2 row_mask:0xf bank_mask:0xf
	v_add_f32_e32 v146, 1.0, v146
	v_rcp_f32_e32 v146, v146
	v_mov_b32_dpp v147, v94 row_shr:2 row_mask:0xf bank_mask:0xf
	v_mul_f32_e32 v145, v145, v146
	v_mul_f32_e32 v252, v144, v145
	v_mov_b32_dpp v146, v90 row_ror:2 row_mask:0xf bank_mask:0xf
	v_mov_b32_dpp v145, v110 row_ror:1 row_mask:0xf bank_mask:0xf
	v_mov_b32_dpp v144, v90 row_ror:1 row_mask:0xf bank_mask:0xf
	v_mov_b32_dpp v146, v74 row_shr:2 row_mask:0xf bank_mask:0xf
	v_mov_b32_dpp v145, v94 row_shr:1 row_mask:0xf bank_mask:0xf
	v_mov_b32_dpp v144, v74 row_shr:1 row_mask:0xf bank_mask:0xf
	v_pk_fma_f32 v[146:147], v[164:165], v[146:147], v[166:167]
	s_nop 0
	v_pk_fma_f32 v[144:145], v[168:169], v[144:145], v[146:147]
	v_mov_b32_e32 v146, v74
	v_mov_b32_e32 v147, v94
	v_pk_fma_f32 v[144:145], v[146:147], v[170:171], v[144:145]
	v_mul_f32_e32 v146, 0x3d372713, v145
	v_mul_f32_e32 v146, v145, v146
	v_fma_f32 v146, v145, v146, v145
	v_mul_f32_e32 v146, 0xbfcc422a, v146
	v_mul_f32_e32 v146, 0x3fb8aa3b, v146
	v_exp_f32_e32 v146, v146
	v_mov_b32_dpp v147, v111 row_ror:2 row_mask:0xf bank_mask:0xf
	v_add_f32_e32 v146, 1.0, v146
	v_rcp_f32_e32 v146, v146
	v_mov_b32_dpp v147, v95 row_shr:2 row_mask:0xf bank_mask:0xf
	v_mul_f32_e32 v145, v145, v146
	v_mul_f32_e32 v253, v144, v145
	v_mov_b32_dpp v146, v91 row_ror:2 row_mask:0xf bank_mask:0xf
	v_mov_b32_dpp v145, v111 row_ror:1 row_mask:0xf bank_mask:0xf
	v_mov_b32_dpp v144, v91 row_ror:1 row_mask:0xf bank_mask:0xf
	v_mov_b32_dpp v146, v75 row_shr:2 row_mask:0xf bank_mask:0xf
	v_mov_b32_dpp v145, v95 row_shr:1 row_mask:0xf bank_mask:0xf
	v_mov_b32_dpp v144, v75 row_shr:1 row_mask:0xf bank_mask:0xf
	v_pk_fma_f32 v[146:147], v[172:173], v[146:147], v[174:175]
	s_nop 0
	v_pk_fma_f32 v[144:145], v[176:177], v[144:145], v[146:147]
	v_mov_b32_e32 v146, v75
	v_mov_b32_e32 v147, v95
	v_pk_fma_f32 v[144:145], v[146:147], v[242:243], v[144:145]
	s_nop 0
	v_mul_f32_e32 v146, 0x3d372713, v145
	v_mul_f32_e32 v146, v145, v146
	v_fma_f32 v146, v145, v146, v145
	v_mul_f32_e32 v146, 0xbfcc422a, v146
	v_mul_f32_e32 v146, 0x3fb8aa3b, v146
	v_exp_f32_e32 v146, v146
	s_nop 0
	v_add_f32_e32 v146, 1.0, v146
	v_rcp_f32_e32 v146, v146
	s_nop 0
	v_mul_f32_e32 v145, v145, v146
	v_mul_f32_e32 v145, v144, v145
	v_mad_i64_i32 v[146:147], s[0:1], v250, s4, v[136:137]
	v_cvt_pk_bf16_f32 v144, v251, v252
	v_cvt_pk_bf16_f32 v145, v253, v145
	v_lshl_add_u64 v[146:147], v[146:147], 0, v[244:245]
	global_store_dwordx4 v[146:147], v[142:145], off
	v_mad_i64_i32 v[136:137], s[0:1], v249, s4, v[136:137]
	s_nop 0
	v_mov_b32_dpp v145, v92 row_ror:2 row_mask:0xf bank_mask:0xf
	v_mov_b32_dpp v144, v72 row_ror:2 row_mask:0xf bank_mask:0xf
	v_mov_b32_dpp v143, v92 row_ror:1 row_mask:0xf bank_mask:0xf
	v_mov_b32_dpp v145, v76 row_shr:2 row_mask:0xf bank_mask:0xf
	v_mov_b32_dpp v142, v72 row_ror:1 row_mask:0xf bank_mask:0xf
; __device__ __forceinline__ unsigned pk2(float lo, float hi) { unsigned r; asm("v_cvt_pk_bf16_f32 %0, %1, %2" : "=v"(r) : "v"(lo), "v"(hi)); return r; }
; __device__ __forceinline__ float gelu_tanh(float x) { const float y = 1.5957691216f * (x + 0.044715f * x * x * x); return x * __builtin_amdgcn_rcpf(1.0f + __expf(-y)); }
;     __device__ __forceinline__ void operator()(const f32x4 (&acc)[2][2][4][2], const Unit& u, int wr, int wc, int fr, int fq) const {
;     ...
;                 for (int m = 0; m < 4; ++m) { const int row = row0 + ai * HALF + m * 16;
;                     const f32x4 g0 = acc[ai][0][m][n], v0 = acc[ai][1][m][n];
;                     f32x4 gp = (f32x4){0.f, 0.f, 0.f, 0.f}, vp = gp;
;                     if (m > 0) { gp = acc[ai][0][m > 0 ? m - 1 : 0][n]; vp = acc[ai][1][m > 0 ? m - 1 : 0][n]; }
;                     f32x4 f;
; #pragma unroll
;                     for (int j = 0; j < 4; ++j) {
;                         const float g1 = dpp_shr1(dpp_ror1(gp[j]), g0[j]), g2 = dpp_shr2(dpp_ror2(gp[j]), g0[j]);
;                         const float v1 = dpp_shr1(dpp_ror1(vp[j]), v0[j]), v2 = dpp_shr2(dpp_ror2(vp[j]), v0[j]);
;                         const float cg_ = bg[j] + g2 * wg0[j] + g1 * wg1[j] + g0[j] * wg2[j];
;                         const float cv_ = bv[j] + v2 * wv0[j] + v1 * wv1[j] + v0[j] * wv2[j];
;                         f[j] = gelu_tanh(cg_) * cv_; }
;                     u32x2 w; w.x = pk2(f[0], f[1]); w.y = pk2(f[2], f[3]);
;                     if (n == 0) res0[ai * 4 + m] = w;
;                     else if (m > 0 || fr >= 2) { u32x4 w4; w4.x = res0[ai * 4 + m].x; w4.y = res0[ai * 4 + m].y; w4.z = w.x; w4.w = w.y; *(u32x4*)(F + (size_t)row * DFF + j0) = w4; }
;                     if (n == 1 && ((m == 0 && fr < 2) || (m == 3 && fr >= 14))) { const int slot = m == 0 ? fr : fr - 12;
;                         const f32x4 ga = acc[ai][0][m][0], va = acc[ai][1][m][0];
;                         bf16_t* bp = UPB + ((size_t)(row >> 6) * 4 + slot) * (2 * DFF) + col0;
;                         u32x4 wg_, wv_; wg_.x = pk2(ga[0], ga[1]); wg_.y = pk2(ga[2], ga[3]); wg_.z = pk2(g0[0], g0[1]); wg_.w = pk2(g0[2], g0[3]);
;                         wv_.x = pk2(va[0], va[1]); wv_.y = pk2(va[2], va[3]); wv_.z = pk2(v0[0], v0[1]); wv_.w = pk2(v0[2], v0[3]);
;                         *(u32x4*)bp = wg_; *(u32x4*)(bp + HALF) = wv_; } }
	v_mov_b32_dpp v144, v64 row_shr:2 row_mask:0xf bank_mask:0xf
	v_mov_b32_dpp v143, v76 row_shr:1 row_mask:0xf bank_mask:0xf
	v_mov_b32_dpp v142, v64 row_shr:1 row_mask:0xf bank_mask:0xf
	v_pk_fma_f32 v[144:145], v[148:149], v[144:145], v[150:151]
	v_lshl_add_u64 v[136:137], v[136:137], 0, v[244:245]
	v_pk_fma_f32 v[142:143], v[152:153], v[142:143], v[144:145]
	v_mov_b32_e32 v144, v64
	v_mov_b32_e32 v145, v76
	v_pk_fma_f32 v[142:143], v[144:145], v[154:155], v[142:143]
	v_mul_f32_e32 v144, 0x3d372713, v143
	v_mul_f32_e32 v144, v143, v144
	v_fma_f32 v144, v143, v144, v143
	v_mul_f32_e32 v144, 0xbfcc422a, v144
	v_mul_f32_e32 v144, 0x3fb8aa3b, v144
	v_exp_f32_e32 v144, v144
	v_mov_b32_dpp v145, v93 row_ror:2 row_mask:0xf bank_mask:0xf
	v_add_f32_e32 v144, 1.0, v144
	v_rcp_f32_e32 v144, v144
	v_mov_b32_dpp v145, v77 row_shr:2 row_mask:0xf bank_mask:0xf
	v_mul_f32_e32 v143, v143, v144
	v_mul_f32_e32 v146, v142, v143
	v_mov_b32_dpp v144, v73 row_ror:2 row_mask:0xf bank_mask:0xf
	v_mov_b32_dpp v143, v93 row_ror:1 row_mask:0xf bank_mask:0xf
	v_mov_b32_dpp v142, v73 row_ror:1 row_mask:0xf bank_mask:0xf
	v_mov_b32_dpp v144, v65 row_shr:2 row_mask:0xf bank_mask:0xf
	v_mov_b32_dpp v143, v77 row_shr:1 row_mask:0xf bank_mask:0xf
	v_mov_b32_dpp v142, v65 row_shr:1 row_mask:0xf bank_mask:0xf
	v_pk_fma_f32 v[144:145], v[156:157], v[144:145], v[158:159]
	s_nop 0
	v_pk_fma_f32 v[142:143], v[160:161], v[142:143], v[144:145]
	v_mov_b32_e32 v144, v65
	v_mov_b32_e32 v145, v77
	v_pk_fma_f32 v[142:143], v[144:145], v[162:163], v[142:143]
	v_mul_f32_e32 v144, 0x3d372713, v143
	v_mul_f32_e32 v144, v143, v144
	v_fma_f32 v144, v143, v144, v143
	v_mul_f32_e32 v144, 0xbfcc422a, v144
	v_mul_f32_e32 v144, 0x3fb8aa3b, v144
	v_exp_f32_e32 v144, v144
	v_mov_b32_dpp v145, v94 row_ror:2 row_mask:0xf bank_mask:0xf
	v_add_f32_e32 v144, 1.0, v144
	v_rcp_f32_e32 v144, v144
	v_mov_b32_dpp v145, v78 row_shr:2 row_mask:0xf bank_mask:0xf
	v_mul_f32_e32 v143, v143, v144
	v_mul_f32_e32 v147, v142, v143
	v_mov_b32_dpp v144, v74 row_ror:2 row_mask:0xf bank_mask:0xf
	v_mov_b32_dpp v143, v94 row_ror:1 row_mask:0xf bank_mask:0xf
	v_mov_b32_dpp v142, v74 row_ror:1 row_mask:0xf bank_mask:0xf
	v_mov_b32_dpp v144, v66 row_shr:2 row_mask:0xf bank_mask:0xf
	v_mov_b32_dpp v143, v78 row_shr:1 row_mask:0xf bank_mask:0xf
	v_mov_b32_dpp v142, v66 row_shr:1 row_mask:0xf bank_mask:0xf
	v_pk_fma_f32 v[144:145], v[164:165], v[144:145], v[166:167]
	s_nop 0
	v_pk_fma_f32 v[142:143], v[168:169], v[142:143], v[144:145]
	v_mov_b32_e32 v144, v66
	v_mov_b32_e32 v145, v78
	v_pk_fma_f32 v[142:143], v[144:145], v[170:171], v[142:143]
	v_mul_f32_e32 v144, 0x3d372713, v143
	v_mul_f32_e32 v144, v143, v144
	v_fma_f32 v144, v143, v144, v143
	v_mul_f32_e32 v144, 0xbfcc422a, v144
	v_mul_f32_e32 v144, 0x3fb8aa3b, v144
	v_exp_f32_e32 v144, v144
	v_mov_b32_dpp v145, v95 row_ror:2 row_mask:0xf bank_mask:0xf
	v_add_f32_e32 v144, 1.0, v144
	v_rcp_f32_e32 v144, v144
	v_mov_b32_dpp v145, v79 row_shr:2 row_mask:0xf bank_mask:0xf
	v_mul_f32_e32 v143, v143, v144
	v_mul_f32_e32 v250, v142, v143
	v_mov_b32_dpp v144, v75 row_ror:2 row_mask:0xf bank_mask:0xf
	v_mov_b32_dpp v143, v95 row_ror:1 row_mask:0xf bank_mask:0xf
	v_mov_b32_dpp v142, v75 row_ror:1 row_mask:0xf bank_mask:0xf
	v_mov_b32_dpp v144, v67 row_shr:2 row_mask:0xf bank_mask:0xf
	v_mov_b32_dpp v143, v79 row_shr:1 row_mask:0xf bank_mask:0xf
	v_mov_b32_dpp v142, v67 row_shr:1 row_mask:0xf bank_mask:0xf
	v_pk_fma_f32 v[144:145], v[172:173], v[144:145], v[174:175]
	s_nop 0
	v_pk_fma_f32 v[142:143], v[176:177], v[142:143], v[144:145]
	v_mov_b32_e32 v144, v67
	v_mov_b32_e32 v145, v79
	v_pk_fma_f32 v[142:143], v[144:145], v[242:243], v[142:143]
	s_nop 0
	v_mul_f32_e32 v144, 0x3d372713, v143
	v_mul_f32_e32 v144, v143, v144
	v_fma_f32 v144, v143, v144, v143
	v_mul_f32_e32 v144, 0xbfcc422a, v144
	v_mul_f32_e32 v144, 0x3fb8aa3b, v144
	v_exp_f32_e32 v144, v144
	s_nop 0
	v_add_f32_e32 v144, 1.0, v144
	v_rcp_f32_e32 v144, v144
	s_nop 0
	v_mul_f32_e32 v143, v143, v144
	v_mul_f32_e32 v143, v142, v143
	v_cvt_pk_bf16_f32 v142, v146, v147
	v_cvt_pk_bf16_f32 v143, v250, v143
	global_store_dwordx4 v[136:137], v[140:143], off
	s_and_saveexec_b64 s[0:1], s[12:13]
	s_cbranch_execz .LBB0_1208
	v_lshl_add_u64 v[136:137], s[72:73], 0, v[234:235]
	v_mov_b64_e32 v[140:141], s[80:81]
	v_mad_u64_u32 v[140:141], s[42:43], v136, s83, v[140:141]
	v_mad_i32_i24 v141, v137, s83, v141
	v_lshl_add_u64 v[136:137], v[240:241], 1, v[140:141]
	v_cvt_pk_bf16_f32 v140, v84, v85
	v_cvt_pk_bf16_f32 v141, v86, v87
	v_cvt_pk_bf16_f32 v142, v76, v77
	v_cvt_pk_bf16_f32 v143, v78, v79
	v_cvt_pk_bf16_f32 v144, v68, v69
	v_cvt_pk_bf16_f32 v145, v70, v71
	v_cvt_pk_bf16_f32 v146, v64, v65
	v_cvt_pk_bf16_f32 v147, v66, v67
	global_store_dwordx4 v[136:137], v[140:143], off
	global_store_dwordx4 v[136:137], v[144:147], off offset:256

; __device__ __forceinline__ unsigned pk2(float lo, float hi) { unsigned r; asm("v_cvt_pk_bf16_f32 %0, %1, %2" : "=v"(r) : "v"(lo), "v"(hi)); return r; }
; __device__ __forceinline__ float gelu_tanh(float x) { const float y = 1.5957691216f * (x + 0.044715f * x * x * x); return x * __builtin_amdgcn_rcpf(1.0f + __expf(-y)); }
; __device__ __forceinline__ float dpp_shr1(float old, float src) { return __int_as_float(__builtin_amdgcn_update_dpp(__float_as_int(old), __float_as_int(src), 0x111, 0xf, 0xf, false)); }
; __device__ __forceinline__ float dpp_shr2(float old, float src) { return __int_as_float(__builtin_amdgcn_update_dpp(__float_as_int(old), __float_as_int(src), 0x112, 0xf, 0xf, false)); }
; __device__ __forceinline__ float dpp_ror1(float src) { return __int_as_float(__builtin_amdgcn_update_dpp(0, __float_as_int(src), 0x121, 0xf, 0xf, false)); }
;     __device__ __forceinline__ void operator()(const f32x4 (&acc)[2][2][4][2], const Unit& u, int wr, int wc, int fr, int fq) const {
;     ...
;                 for (int m = 0; m < 4; ++m) { const int row = row0 + ai * HALF + m * 16;
;                     const f32x4 g0 = acc[ai][0][m][n], v0 = acc[ai][1][m][n];
;                     f32x4 gp = (f32x4){0.f, 0.f, 0.f, 0.f}, vp = gp;
;                     if (m > 0) { gp = acc[ai][0][m > 0 ? m - 1 : 0][n]; vp = acc[ai][1][m > 0 ? m - 1 : 0][n]; }
;                     f32x4 f;
; #pragma unroll
;                     for (int j = 0; j < 4; ++j) {
;                         const float g1 = dpp_shr1(dpp_ror1(gp[j]), g0[j]), g2 = dpp_shr2(dpp_ror2(gp[j]), g0[j]);
;                         const float v1 = dpp_shr1(dpp_ror1(vp[j]), v0[j]), v2 = dpp_shr2(dpp_ror2(vp[j]), v0[j]);
;                         const float cg_ = bg[j] + g2 * wg0[j] + g1 * wg1[j] + g0[j] * wg2[j];
;                         const float cv_ = bv[j] + v2 * wv0[j] + v1 * wv1[j] + v0[j] * wv2[j];
;                         f[j] = gelu_tanh(cg_) * cv_; }
;                     u32x2 w; w.x = pk2(f[0], f[1]); w.y = pk2(f[2], f[3]);
;                     if (n == 0) res0[ai * 4 + m] = w;
;                     else if (m > 0 || fr >= 2) { u32x4 w4; w4.x = res0[ai * 4 + m].x; w4.y = res0[ai * 4 + m].y; w4.z = w.x; w4.w = w.y; *(u32x4*)(F + (size_t)row * DFF + j0) = w4; }
.LBB0_1212:
	s_or_b64 exec, exec, s[0:1]
	v_mov_b32_dpp v135, v56 row_ror:2 row_mask:0xf bank_mask:0xf
	v_mov_b32_dpp v134, v40 row_ror:2 row_mask:0xf bank_mask:0xf
	v_mov_b32_dpp v131, v56 row_ror:1 row_mask:0xf bank_mask:0xf
	v_mov_b32_dpp v135, v44 row_shr:2 row_mask:0xf bank_mask:0xf
	v_mov_b32_dpp v130, v40 row_ror:1 row_mask:0xf bank_mask:0xf
	v_mov_b32_dpp v134, v24 row_shr:2 row_mask:0xf bank_mask:0xf
	v_mov_b32_dpp v131, v44 row_shr:1 row_mask:0xf bank_mask:0xf
	v_mov_b32_dpp v130, v24 row_shr:1 row_mask:0xf bank_mask:0xf
	v_pk_fma_f32 v[134:135], v[148:149], v[134:135], v[150:151]
	v_pk_fma_f32 v[130:131], v[152:153], v[130:131], v[134:135]
	v_mov_b32_e32 v134, v24
	v_mov_b32_e32 v135, v44
	v_pk_fma_f32 v[130:131], v[134:135], v[154:155], v[130:131]
	v_mul_f32_e32 v134, 0x3d372713, v131
	v_mul_f32_e32 v134, v131, v134
	v_fma_f32 v134, v131, v134, v131
	v_mul_f32_e32 v134, 0xbfcc422a, v134
	v_mul_f32_e32 v134, 0x3fb8aa3b, v134
	v_exp_f32_e32 v134, v134
	v_mov_b32_dpp v141, v57 row_ror:2 row_mask:0xf bank_mask:0xf
	v_mov_b32_dpp v140, v41 row_ror:2 row_mask:0xf bank_mask:0xf
	v_add_f32_e32 v134, 1.0, v134
	v_rcp_f32_e32 v142, v134
	v_mov_b32_dpp v135, v57 row_ror:1 row_mask:0xf bank_mask:0xf
	v_mov_b32_dpp v141, v45 row_shr:2 row_mask:0xf bank_mask:0xf
	v_mov_b32_dpp v134, v41 row_ror:1 row_mask:0xf bank_mask:0xf
	v_mov_b32_dpp v140, v25 row_shr:2 row_mask:0xf bank_mask:0xf
	v_mov_b32_dpp v135, v45 row_shr:1 row_mask:0xf bank_mask:0xf
	v_mov_b32_dpp v134, v25 row_shr:1 row_mask:0xf bank_mask:0xf
	v_pk_fma_f32 v[140:141], v[156:157], v[140:141], v[158:159]
	v_mul_f32_e32 v131, v131, v142
	v_pk_fma_f32 v[134:135], v[160:161], v[134:135], v[140:141]
	v_mov_b32_e32 v140, v25
	v_mov_b32_e32 v141, v45
	v_pk_fma_f32 v[134:135], v[140:141], v[162:163], v[134:135]
	v_mul_f32_e32 v145, v130, v131
	v_mul_f32_e32 v140, 0x3d372713, v135
	v_mul_f32_e32 v140, v135, v140
	v_fma_f32 v140, v135, v140, v135
	v_mul_f32_e32 v140, 0xbfcc422a, v140
	v_mul_f32_e32 v140, 0x3fb8aa3b, v140
	v_exp_f32_e32 v140, v140
	s_nop 0
	v_add_f32_e32 v130, 1.0, v140
	v_rcp_f32_e32 v146, v130
	v_mov_b32_dpp v141, v58 row_ror:2 row_mask:0xf bank_mask:0xf
	v_mov_b32_dpp v140, v42 row_ror:2 row_mask:0xf bank_mask:0xf
	v_mov_b32_dpp v131, v58 row_ror:1 row_mask:0xf bank_mask:0xf
	v_mov_b32_dpp v141, v46 row_shr:2 row_mask:0xf bank_mask:0xf
	v_mov_b32_dpp v130, v42 row_ror:1 row_mask:0xf bank_mask:0xf
	v_mov_b32_dpp v140, v26 row_shr:2 row_mask:0xf bank_mask:0xf
	v_mov_b32_dpp v131, v46 row_shr:1 row_mask:0xf bank_mask:0xf
	v_mov_b32_dpp v130, v26 row_shr:1 row_mask:0xf bank_mask:0xf
	v_pk_fma_f32 v[140:141], v[164:165], v[140:141], v[166:167]
	v_pk_fma_f32 v[130:131], v[168:169], v[130:131], v[140:141]
	v_mov_b32_e32 v140, v26
	v_mov_b32_e32 v141, v46
	v_pk_fma_f32 v[130:131], v[140:141], v[170:171], v[130:131]
	v_mul_f32_e32 v140, 0x3d372713, v131
	v_mul_f32_e32 v140, v131, v140
	v_fma_f32 v140, v131, v140, v131
	v_mul_f32_e32 v140, 0xbfcc422a, v140
	v_mul_f32_e32 v140, 0x3fb8aa3b, v140
	v_exp_f32_e32 v147, v140
	v_mov_b32_dpp v143, v59 row_ror:2 row_mask:0xf bank_mask:0xf
	v_mov_b32_dpp v142, v43 row_ror:2 row_mask:0xf bank_mask:0xf
	v_mov_b32_dpp v141, v59 row_ror:1 row_mask:0xf bank_mask:0xf
	v_mov_b32_dpp v143, v47 row_shr:2 row_mask:0xf bank_mask:0xf
	v_mov_b32_dpp v140, v43 row_ror:1 row_mask:0xf bank_mask:0xf
	v_mov_b32_dpp v142, v27 row_shr:2 row_mask:0xf bank_mask:0xf
	v_mov_b32_dpp v141, v47 row_shr:1 row_mask:0xf bank_mask:0xf
	v_mov_b32_dpp v140, v27 row_shr:1 row_mask:0xf bank_mask:0xf
	v_pk_fma_f32 v[142:143], v[172:173], v[142:143], v[174:175]
	v_mul_f32_e32 v135, v135, v146
	v_pk_fma_f32 v[140:141], v[176:177], v[140:141], v[142:143]
	v_mov_b32_e32 v142, v27
	v_mov_b32_e32 v143, v47
	v_pk_fma_f32 v[140:141], v[142:143], v[242:243], v[140:141]
	v_add_f32_e32 v143, 1.0, v147
	v_mul_f32_e32 v142, 0x3d372713, v141
	v_mul_f32_e32 v142, v141, v142
	v_fma_f32 v142, v141, v142, v141
	v_mul_f32_e32 v142, 0xbfcc422a, v142
	v_mul_f32_e32 v142, 0x3fb8aa3b, v142
	v_exp_f32_e32 v142, v142
	v_rcp_f32_e32 v143, v143
	v_mul_f32_e32 v134, v134, v135
	v_add_u32_e32 v144, 0x90, v248
	v_add_f32_e32 v142, 1.0, v142
	v_rcp_f32_e32 v142, v142
	v_mul_f32_e32 v131, v131, v143
	v_mul_f32_e32 v131, v130, v131
	v_mul_f32_e32 v130, v141, v142
	v_mul_f32_e32 v135, v140, v130
	v_cvt_pk_bf16_f32 v130, v145, v134
	v_cvt_pk_bf16_f32 v131, v131, v135
	v_mov_b32_dpp v141, v44 row_ror:2 row_mask:0xf bank_mask:0xf
	v_mov_b32_dpp v140, v24 row_ror:2 row_mask:0xf bank_mask:0xf
	v_mov_b32_dpp v135, v44 row_ror:1 row_mask:0xf bank_mask:0xf
	v_mov_b32_dpp v141, v28 row_shr:2 row_mask:0xf bank_mask:0xf
	v_mov_b32_dpp v134, v24 row_ror:1 row_mask:0xf bank_mask:0xf
	v_mov_b32_dpp v140, v8 row_shr:2 row_mask:0xf bank_mask:0xf
	v_mov_b32_dpp v135, v28 row_shr:1 row_mask:0xf bank_mask:0xf
	v_mov_b32_dpp v134, v8 row_shr:1 row_mask:0xf bank_mask:0xf
	v_pk_fma_f32 v[140:141], v[148:149], v[140:141], v[150:151]
	v_mov_b64_e32 v[142:143], s[40:41]
	v_pk_fma_f32 v[134:135], v[152:153], v[134:135], v[140:141]
	v_mov_b32_e32 v140, v8
	v_mov_b32_e32 v141, v28
	v_pk_fma_f32 v[134:135], v[140:141], v[154:155], v[134:135]
	v_mul_f32_e32 v140, 0x3d372713, v135
	v_mul_f32_e32 v140, v135, v140
	v_fma_f32 v140, v135, v140, v135
	v_mul_f32_e32 v140, 0xbfcc422a, v140
	v_mul_f32_e32 v140, 0x3fb8aa3b, v140
	v_exp_f32_e32 v145, v140
	v_mad_i64_i32 v[140:141], s[0:1], v144, s4, v[142:143]
	v_mov_b32_dpp v147, v45 row_ror:2 row_mask:0xf bank_mask:0xf
	v_add_f32_e32 v144, 1.0, v145
	v_rcp_f32_e32 v180, v144
	v_mov_b32_dpp v146, v25 row_ror:2 row_mask:0xf bank_mask:0xf
	v_mov_b32_dpp v145, v45 row_ror:1 row_mask:0xf bank_mask:0xf
; __device__ __forceinline__ unsigned pk2(float lo, float hi) { unsigned r; asm("v_cvt_pk_bf16_f32 %0, %1, %2" : "=v"(r) : "v"(lo), "v"(hi)); return r; }
; __device__ __forceinline__ float gelu_tanh(float x) { const float y = 1.5957691216f * (x + 0.044715f * x * x * x); return x * __builtin_amdgcn_rcpf(1.0f + __expf(-y)); }
; __device__ __forceinline__ float dpp_shr1(float old, float src) { return __int_as_float(__builtin_amdgcn_update_dpp(__float_as_int(old), __float_as_int(src), 0x111, 0xf, 0xf, false)); }
; __device__ __forceinline__ float dpp_shr2(float old, float src) { return __int_as_float(__builtin_amdgcn_update_dpp(__float_as_int(old), __float_as_int(src), 0x112, 0xf, 0xf, false)); }
; __device__ __forceinline__ float dpp_ror1(float src) { return __int_as_float(__builtin_amdgcn_update_dpp(0, __float_as_int(src), 0x121, 0xf, 0xf, false)); }
;     __device__ __forceinline__ void operator()(const f32x4 (&acc)[2][2][4][2], const Unit& u, int wr, int wc, int fr, int fq) const {
;     ...
;                 for (int m = 0; m < 4; ++m) { const int row = row0 + ai * HALF + m * 16;
;                     const f32x4 g0 = acc[ai][0][m][n], v0 = acc[ai][1][m][n];
;                     f32x4 gp = (f32x4){0.f, 0.f, 0.f, 0.f}, vp = gp;
;                     if (m > 0) { gp = acc[ai][0][m > 0 ? m - 1 : 0][n]; vp = acc[ai][1][m > 0 ? m - 1 : 0][n]; }
;                     f32x4 f;
; #pragma unroll
;                     for (int j = 0; j < 4; ++j) {
;                         const float g1 = dpp_shr1(dpp_ror1(gp[j]), g0[j]), g2 = dpp_shr2(dpp_ror2(gp[j]), g0[j]);
;                         const float v1 = dpp_shr1(dpp_ror1(vp[j]), v0[j]), v2 = dpp_shr2(dpp_ror2(vp[j]), v0[j]);
;                         const float cg_ = bg[j] + g2 * wg0[j] + g1 * wg1[j] + g0[j] * wg2[j];
;                         const float cv_ = bv[j] + v2 * wv0[j] + v1 * wv1[j] + v0[j] * wv2[j];
;                         f[j] = gelu_tanh(cg_) * cv_; }
;                     u32x2 w; w.x = pk2(f[0], f[1]); w.y = pk2(f[2], f[3]);
;                     if (n == 0) res0[ai * 4 + m] = w;
;                     else if (m > 0 || fr >= 2) { u32x4 w4; w4.x = res0[ai * 4 + m].x; w4.y = res0[ai * 4 + m].y; w4.z = w.x; w4.w = w.y; *(u32x4*)(F + (size_t)row * DFF + j0) = w4; }
	v_mov_b32_dpp v147, v29 row_shr:2 row_mask:0xf bank_mask:0xf
	v_mov_b32_dpp v144, v25 row_ror:1 row_mask:0xf bank_mask:0xf
	v_mov_b32_dpp v146, v9 row_shr:2 row_mask:0xf bank_mask:0xf
	v_mov_b32_dpp v145, v29 row_shr:1 row_mask:0xf bank_mask:0xf
	v_mov_b32_dpp v144, v9 row_shr:1 row_mask:0xf bank_mask:0xf
	v_pk_fma_f32 v[146:147], v[156:157], v[146:147], v[158:159]
	v_lshl_add_u64 v[140:141], v[140:141], 0, v[244:245]
	v_pk_fma_f32 v[144:145], v[160:161], v[144:145], v[146:147]
	v_mov_b32_e32 v146, v9
	v_mov_b32_e32 v147, v29
	v_pk_fma_f32 v[144:145], v[146:147], v[162:163], v[144:145]
	global_store_dwordx4 v[140:141], v[128:131], off
	v_mul_f32_e32 v146, 0x3d372713, v145
	v_mul_f32_e32 v146, v145, v146
	v_fma_f32 v146, v145, v146, v145
	v_mul_f32_e32 v146, 0xbfcc422a, v146
	v_mul_f32_e32 v146, 0x3fb8aa3b, v146
	v_exp_f32_e32 v146, v146
	v_mul_f32_e32 v128, v135, v180
	v_mul_f32_e32 v140, v134, v128
	v_add_f32_e32 v128, 1.0, v146
	v_rcp_f32_e32 v141, v128
	v_mov_b32_dpp v131, v46 row_ror:2 row_mask:0xf bank_mask:0xf
	v_mov_b32_dpp v130, v26 row_ror:2 row_mask:0xf bank_mask:0xf
	v_mov_b32_dpp v129, v46 row_ror:1 row_mask:0xf bank_mask:0xf
	v_mov_b32_dpp v131, v30 row_shr:2 row_mask:0xf bank_mask:0xf
	v_mov_b32_dpp v128, v26 row_ror:1 row_mask:0xf bank_mask:0xf
	v_mov_b32_dpp v130, v10 row_shr:2 row_mask:0xf bank_mask:0xf
	v_mov_b32_dpp v129, v30 row_shr:1 row_mask:0xf bank_mask:0xf
	v_mov_b32_dpp v128, v10 row_shr:1 row_mask:0xf bank_mask:0xf
	v_pk_fma_f32 v[130:131], v[164:165], v[130:131], v[166:167]
	v_pk_fma_f32 v[128:129], v[168:169], v[128:129], v[130:131]
	v_mov_b32_e32 v130, v10
	v_mov_b32_e32 v131, v30
	v_pk_fma_f32 v[128:129], v[130:131], v[170:171], v[128:129]
	v_mul_f32_e32 v130, 0x3d372713, v129
	v_mul_f32_e32 v130, v129, v130
	v_fma_f32 v130, v129, v130, v129
	v_mul_f32_e32 v130, 0xbfcc422a, v130
	v_mul_f32_e32 v130, 0x3fb8aa3b, v130
	v_exp_f32_e32 v146, v130
	v_mov_b32_dpp v135, v47 row_ror:2 row_mask:0xf bank_mask:0xf
	v_mov_b32_dpp v134, v27 row_ror:2 row_mask:0xf bank_mask:0xf
	v_mov_b32_dpp v131, v47 row_ror:1 row_mask:0xf bank_mask:0xf
	v_mov_b32_dpp v135, v31 row_shr:2 row_mask:0xf bank_mask:0xf
	v_mov_b32_dpp v130, v27 row_ror:1 row_mask:0xf bank_mask:0xf
	v_mov_b32_dpp v134, v11 row_shr:2 row_mask:0xf bank_mask:0xf
	v_mov_b32_dpp v131, v31 row_shr:1 row_mask:0xf bank_mask:0xf
	v_mov_b32_dpp v130, v11 row_shr:1 row_mask:0xf bank_mask:0xf
	v_pk_fma_f32 v[134:135], v[172:173], v[134:135], v[174:175]
	v_add_u32_e32 v178, 0xa0, v248
	v_pk_fma_f32 v[130:131], v[176:177], v[130:131], v[134:135]
	v_mov_b32_e32 v134, v11
	v_mov_b32_e32 v135, v31
	v_pk_fma_f32 v[130:131], v[134:135], v[242:243], v[130:131]
	v_mul_f32_e32 v135, v145, v141
	v_mul_f32_e32 v134, 0x3d372713, v131
	v_mul_f32_e32 v134, v131, v134
	v_fma_f32 v134, v131, v134, v131
	v_mul_f32_e32 v134, 0xbfcc422a, v134
	v_mul_f32_e32 v134, 0x3fb8aa3b, v134
	v_exp_f32_e32 v134, v134
	v_add_f32_e32 v141, 1.0, v146
	v_rcp_f32_e32 v141, v141
	v_mul_f32_e32 v135, v144, v135
	v_add_f32_e32 v134, 1.0, v134
	v_rcp_f32_e32 v134, v134
	v_mul_f32_e32 v129, v129, v141
	v_mul_f32_e32 v128, v128, v129
	v_mul_f32_e32 v129, v131, v134
	v_mul_f32_e32 v129, v130, v129
	v_cvt_pk_bf16_f32 v134, v140, v135
	v_cvt_pk_bf16_f32 v135, v128, v129
	v_mov_b32_dpp v131, v28 row_ror:2 row_mask:0xf bank_mask:0xf
	v_mov_b32_dpp v130, v8 row_ror:2 row_mask:0xf bank_mask:0xf
	v_mov_b32_dpp v129, v28 row_ror:1 row_mask:0xf bank_mask:0xf
	v_mov_b32_dpp v131, v12 row_shr:2 row_mask:0xf bank_mask:0xf
	v_mov_b32_dpp v128, v8 row_ror:1 row_mask:0xf bank_mask:0xf
	v_mov_b32_dpp v130, v0 row_shr:2 row_mask:0xf bank_mask:0xf
	v_mov_b32_dpp v129, v12 row_shr:1 row_mask:0xf bank_mask:0xf
	v_mov_b32_dpp v128, v0 row_shr:1 row_mask:0xf bank_mask:0xf
	v_pk_fma_f32 v[130:131], v[148:149], v[130:131], v[150:151]
	v_pk_fma_f32 v[128:129], v[152:153], v[128:129], v[130:131]
	v_mov_b32_e32 v130, v0
	v_mov_b32_e32 v131, v12
	v_pk_fma_f32 v[128:129], v[130:131], v[154:155], v[128:129]
	v_mul_f32_e32 v130, 0x3d372713, v129
	v_mul_f32_e32 v130, v129, v130
	v_fma_f32 v130, v129, v130, v129
	v_mul_f32_e32 v130, 0xbfcc422a, v130
	v_mul_f32_e32 v130, 0x3fb8aa3b, v130
	v_exp_f32_e32 v140, v130
	v_mov_b32_dpp v145, v29 row_ror:2 row_mask:0xf bank_mask:0xf
	v_mov_b32_dpp v144, v9 row_ror:2 row_mask:0xf bank_mask:0xf
; __device__ __forceinline__ unsigned pk2(float lo, float hi) { unsigned r; asm("v_cvt_pk_bf16_f32 %0, %1, %2" : "=v"(r) : "v"(lo), "v"(hi)); return r; }
; __device__ __forceinline__ float gelu_tanh(float x) { const float y = 1.5957691216f * (x + 0.044715f * x * x * x); return x * __builtin_amdgcn_rcpf(1.0f + __expf(-y)); }
;     __device__ __forceinline__ void operator()(const f32x4 (&acc)[2][2][4][2], const Unit& u, int wr, int wc, int fr, int fq) const {
;     ...
;                 for (int m = 0; m < 4; ++m) { const int row = row0 + ai * HALF + m * 16;
;                     const f32x4 g0 = acc[ai][0][m][n], v0 = acc[ai][1][m][n];
;                     f32x4 gp = (f32x4){0.f, 0.f, 0.f, 0.f}, vp = gp;
;                     if (m > 0) { gp = acc[ai][0][m > 0 ? m - 1 : 0][n]; vp = acc[ai][1][m > 0 ? m - 1 : 0][n]; }
;                     f32x4 f;
; #pragma unroll
;                     for (int j = 0; j < 4; ++j) {
;                         const float g1 = dpp_shr1(dpp_ror1(gp[j]), g0[j]), g2 = dpp_shr2(dpp_ror2(gp[j]), g0[j]);
;                         const float v1 = dpp_shr1(dpp_ror1(vp[j]), v0[j]), v2 = dpp_shr2(dpp_ror2(vp[j]), v0[j]);
;                         const float cg_ = bg[j] + g2 * wg0[j] + g1 * wg1[j] + g0[j] * wg2[j];
;                         const float cv_ = bv[j] + v2 * wv0[j] + v1 * wv1[j] + v0[j] * wv2[j];
;                         f[j] = gelu_tanh(cg_) * cv_; }
;                     u32x2 w; w.x = pk2(f[0], f[1]); w.y = pk2(f[2], f[3]);
;                     if (n == 0) res0[ai * 4 + m] = w;
;                     else if (m > 0 || fr >= 2) { u32x4 w4; w4.x = res0[ai * 4 + m].x; w4.y = res0[ai * 4 + m].y; w4.z = w.x; w4.w = w.y; *(u32x4*)(F + (size_t)row * DFF + j0) = w4; }
;                     if (n == 1 && ((m == 0 && fr < 2) || (m == 3 && fr >= 14))) { const int slot = m == 0 ? fr : fr - 12;
;                         const f32x4 ga = acc[ai][0][m][0], va = acc[ai][1][m][0];
;                         bf16_t* bp = UPB + ((size_t)(row >> 6) * 4 + slot) * (2 * DFF) + col0;
;                         u32x4 wg_, wv_; wg_.x = pk2(ga[0], ga[1]); wg_.y = pk2(ga[2], ga[3]); wg_.z = pk2(g0[0], g0[1]); wg_.w = pk2(g0[2], g0[3]);
;                         wv_.x = pk2(va[0], va[1]); wv_.y = pk2(va[2], va[3]); wv_.z = pk2(v0[0], v0[1]); wv_.w = pk2(v0[2], v0[3]);
;                         *(u32x4*)bp = wg_; *(u32x4*)(bp + HALF) = wv_; } }
	v_mov_b32_dpp v141, v29 row_ror:1 row_mask:0xf bank_mask:0xf
	v_add_f32_e32 v140, 1.0, v140
	v_rcp_f32_e32 v146, v140
	v_mov_b32_dpp v145, v13 row_shr:2 row_mask:0xf bank_mask:0xf
	v_mov_b32_dpp v144, v1 row_shr:2 row_mask:0xf bank_mask:0xf
	v_mov_b32_dpp v140, v9 row_ror:1 row_mask:0xf bank_mask:0xf
	v_mov_b32_dpp v141, v13 row_shr:1 row_mask:0xf bank_mask:0xf
	v_pk_fma_f32 v[144:145], v[156:157], v[144:145], v[158:159]
	v_mov_b32_dpp v140, v1 row_shr:1 row_mask:0xf bank_mask:0xf
	v_pk_fma_f32 v[140:141], v[160:161], v[140:141], v[144:145]
	v_mov_b32_e32 v144, v1
	v_mov_b32_e32 v145, v13
	v_pk_fma_f32 v[140:141], v[144:145], v[162:163], v[140:141]
	v_mad_i64_i32 v[130:131], s[0:1], v178, s4, v[142:143]
	v_mul_f32_e32 v144, 0x3d372713, v141
	v_mul_f32_e32 v144, v141, v144
	v_fma_f32 v144, v141, v144, v141
	v_mul_f32_e32 v144, 0xbfcc422a, v144
	v_mul_f32_e32 v144, 0x3fb8aa3b, v144
	v_exp_f32_e32 v144, v144
	v_lshl_add_u64 v[130:131], v[130:131], 0, v[244:245]
	v_mul_f32_e32 v129, v129, v146
	global_store_dwordx4 v[130:131], v[132:135], off
	s_nop 1
	v_mul_f32_e32 v134, v128, v129
	v_add_f32_e32 v128, 1.0, v144
	v_rcp_f32_e32 v135, v128
	v_mov_b32_dpp v131, v30 row_ror:2 row_mask:0xf bank_mask:0xf
	v_mov_b32_dpp v130, v10 row_ror:2 row_mask:0xf bank_mask:0xf
	v_mov_b32_dpp v129, v30 row_ror:1 row_mask:0xf bank_mask:0xf
	v_mov_b32_dpp v131, v14 row_shr:2 row_mask:0xf bank_mask:0xf
	v_mov_b32_dpp v128, v10 row_ror:1 row_mask:0xf bank_mask:0xf
	v_mov_b32_dpp v130, v2 row_shr:2 row_mask:0xf bank_mask:0xf
	v_mov_b32_dpp v129, v14 row_shr:1 row_mask:0xf bank_mask:0xf
	v_mov_b32_dpp v128, v2 row_shr:1 row_mask:0xf bank_mask:0xf
	v_pk_fma_f32 v[130:131], v[164:165], v[130:131], v[166:167]
	v_pk_fma_f32 v[128:129], v[168:169], v[128:129], v[130:131]
	v_mov_b32_e32 v130, v2
	v_mov_b32_e32 v131, v14
	v_pk_fma_f32 v[128:129], v[130:131], v[170:171], v[128:129]
	v_mul_f32_e32 v130, 0x3d372713, v129
	v_mul_f32_e32 v130, v129, v130
	v_fma_f32 v130, v129, v130, v129
	v_mul_f32_e32 v130, 0xbfcc422a, v130
	v_mul_f32_e32 v130, 0x3fb8aa3b, v130
	v_exp_f32_e32 v144, v130
	v_mov_b32_dpp v133, v31 row_ror:2 row_mask:0xf bank_mask:0xf
	v_mov_b32_dpp v132, v11 row_ror:2 row_mask:0xf bank_mask:0xf
	v_mov_b32_dpp v131, v31 row_ror:1 row_mask:0xf bank_mask:0xf
	v_mov_b32_dpp v133, v15 row_shr:2 row_mask:0xf bank_mask:0xf
	v_mov_b32_dpp v130, v11 row_ror:1 row_mask:0xf bank_mask:0xf
	v_mov_b32_dpp v132, v3 row_shr:2 row_mask:0xf bank_mask:0xf
	v_mov_b32_dpp v131, v15 row_shr:1 row_mask:0xf bank_mask:0xf
	v_mov_b32_dpp v130, v3 row_shr:1 row_mask:0xf bank_mask:0xf
	v_pk_fma_f32 v[132:133], v[172:173], v[132:133], v[174:175]
	v_add_u32_e32 v179, 0xb0, v248
	v_pk_fma_f32 v[130:131], v[176:177], v[130:131], v[132:133]
	v_mov_b32_e32 v132, v3
	v_mov_b32_e32 v133, v15
	v_pk_fma_f32 v[130:131], v[132:133], v[242:243], v[130:131]
	v_mul_f32_e32 v133, v141, v135
	v_mul_f32_e32 v132, 0x3d372713, v131
	v_mul_f32_e32 v132, v131, v132
	v_fma_f32 v132, v131, v132, v131
	v_mul_f32_e32 v132, 0xbfcc422a, v132
	v_mul_f32_e32 v132, 0x3fb8aa3b, v132
	v_exp_f32_e32 v132, v132
	v_add_f32_e32 v135, 1.0, v144
	v_rcp_f32_e32 v135, v135
	v_mul_f32_e32 v133, v140, v133
	v_add_f32_e32 v132, 1.0, v132
	v_rcp_f32_e32 v132, v132
	v_mul_f32_e32 v129, v129, v135
	v_mul_f32_e32 v128, v128, v129
	s_mov_b64 s[72:73], 0
	v_mul_f32_e32 v129, v131, v132
	v_mul_f32_e32 v129, v130, v129
	v_cvt_pk_bf16_f32 v141, v128, v129
	v_mad_i64_i32 v[128:129], s[0:1], v179, s4, v[142:143]
	v_lshl_add_u64 v[128:129], v[128:129], 0, v[244:245]
	s_mov_b64 s[0:1], 0
	v_cvt_pk_bf16_f32 v140, v134, v133
	global_store_dwordx4 v[128:129], v[138:141], off
	s_and_saveexec_b64 s[42:43], s[12:13]
	s_xor_b64 s[52:53], exec, s[42:43]
	s_cbranch_execz .LBB0_1214
	v_lshl_add_u64 v[128:129], v[136:137], 0, v[234:235]
	v_mov_b64_e32 v[130:131], s[80:81]
	v_mad_u64_u32 v[130:131], s[42:43], v128, s83, v[130:131]
	v_mad_i32_i24 v131, v129, s83, v131
	v_lshl_add_u64 v[132:133], v[240:241], 1, v[130:131]
	s_mov_b64 s[72:73], exec
	v_cvt_pk_bf16_f32 v134, v20, v21
	v_cvt_pk_bf16_f32 v135, v22, v23
	v_cvt_pk_bf16_f32 v136, v12, v13
	v_cvt_pk_bf16_f32 v137, v14, v15
	v_cvt_pk_bf16_f32 v128, v4, v5
	v_cvt_pk_bf16_f32 v129, v6, v7
	v_cvt_pk_bf16_f32 v130, v0, v1
	v_cvt_pk_bf16_f32 v131, v2, v3
	global_store_dwordx4 v[132:133], v[134:137], off
